# P5 q/k-head epilogue: rotary-table rows fetched one 16-row group ahead into dead fragment regs (counted vmcnt, no store drain), 4 norm-weight loads issued together
# baseline (speedup 1.0000x reference)
; __device__ __forceinline__ float dot4(f32x4 v) { return (v[0] * v[0] + v[1] * v[1]) + (v[2] * v[2] + v[3] * v[3]); }
; __device__ __forceinline__ float quad_sum(float s) { s += __shfl_xor(s, 16); s += __shfl_xor(s, 32); return s; }
; __device__ __forceinline__ void st4(bf16_t* p, f32x4 v) { u32x2 w; w.x = cvt_pk_bf16(v[0], v[1]); w.y = cvt_pk_bf16(v[2], v[3]); *(u32x2*)p = w; }
;     __device__ __forceinline__ void operator()(const f32x4 (&acc)[2][2][4][2], const Unit& u, int wr, int wc, int fr, int fq) const {
;     ...
;             const bool isq = u.pn <= 2; const float* g = isq ? gq : gk;
;             bf16_t* dst = isq ? QG + (4 * (u.pn - 1) + wc) * 64 : KG + wc * 64; const int pitch = isq ? 512 : 128; const float osc = isq ? C2G : 1.f;
;             f32x4 gv[2][2];
; #pragma unroll
;             for (int bj = 0; bj < 2; ++bj)
; #pragma unroll
;                 for (int n = 0; n < 2; ++n) gv[bj][n] = *(const f32x4*)(g + 32 * bj + 16 * n + 4 * fq) * osc;
; #pragma unroll
;             for (int ai = 0; ai < 2; ++ai)
; #pragma unroll
;                 for (int m = 0; m < 4; ++m) { const int row = row0 + ai * HALF + m * 16; float s = 0.f;
; #pragma unroll
;                     for (int bj = 0; bj < 2; ++bj)
; #pragma unroll
;                         for (int n = 0; n < 2; ++n) s += dot4(acc[ai][bj][m][n]);
;                     s = quad_sum(s); const float rstd = 1.0f / sqrtf(s * (1.f / 64.f) + NEPS);
;                     const int srow = row & (SEQL - 1), prow = srow >> 6, pcol = srow & 63;
; #pragma unroll
;                     for (int bj = 0; bj < 2; ++bj) { const int pos = bj ? pcol : prow; f32x4 y1, y2;
;                         rope4(acc[ai][bj][m][0] * rstd * gv[bj][0], acc[ai][bj][m][1] * rstd * gv[bj][1], ropeG + (pos * 16 + 4 * fq) * 2, y1, y2);
;                         bf16_t* dp = isq ? dst + (size_t)row * pitch : KG + ((((size_t)((row >> 12) * 2 + wc) * 64 + (srow >> 6)) * 64 + (srow & 63)) * 64);
;                         st4(dp + 32 * bj + 4 * fq, y1); st4(dp + 32 * bj + 16 + 4 * fq, y2); } }
.LBB0_530:
	v_lshlrev_b32_e32 v168, 2, v199
	v_ashrrev_i32_e32 v169, 31, v168
	v_lshl_add_u64 v[132:133], v[168:169], 2, s[96:97]
	global_load_dwordx4 v[128:131], v[132:133], off
	global_load_dwordx4 v[222:225], v[132:133], off offset:64
	global_load_dwordx4 v[226:229], v[132:133], off offset:128
	global_load_dwordx4 v[230:233], v[132:133], off offset:192
	s_lshl_b32 s1, s94, 8
	v_readlane_b32 s7, v255, 58
	s_add_i32 s10, s7, s1
	s_ashr_i32 s11, s10, 31
	s_lshl_b64 s[10:11], s[10:11], 1
	s_add_u32 s1, s40, s10
	s_addc_u32 s7, s41, s11
	s_and_b64 s[10:11], exec, s[92:93]
	v_readlane_b32 s10, v255, 57
	s_cselect_b32 s11, s7, s10
	v_readlane_b32 s7, v255, 56
	s_cselect_b32 s10, s1, s7
	v_and_b32_e32 v205, 63, v184
	v_lshlrev_b32_e32 v151, 3, v199
	v_readlane_b32 s58, v255, 24
	v_readlane_b32 s59, v255, 25
	v_bitop3_b32 v203, v184, 32, 63 bitop3:0x6c
	v_lshlrev_b64 v[168:169], 1, v[168:169]
	s_waitcnt vmcnt(3)
	v_pk_mul_f32 v[160:161], s[0:1], v[130:131] op_sel_hi:[0,1]
	v_pk_mul_f32 v[162:163], s[0:1], v[128:129] op_sel_hi:[0,1]
	s_waitcnt vmcnt(2)
	v_pk_mul_f32 v[164:165], s[0:1], v[224:225] op_sel_hi:[0,1]
	v_pk_mul_f32 v[166:167], s[0:1], v[222:223] op_sel_hi:[0,1]
	s_waitcnt vmcnt(1)
	v_pk_mul_f32 v[152:153], s[0:1], v[228:229] op_sel_hi:[0,1]
	v_pk_mul_f32 v[158:159], s[0:1], v[226:227] op_sel_hi:[0,1]
	s_waitcnt vmcnt(0)
	v_pk_mul_f32 v[156:157], s[0:1], v[230:231] op_sel_hi:[0,1]
	v_and_b32_e32 v129, 64, v198
	v_xor_b32_e32 v128, 16, v198
	v_add_u32_e32 v129, 64, v129
	v_cmp_lt_i32_e32 vcc, v128, v129
	v_pk_mul_f32 v[154:155], s[0:1], v[232:233] op_sel_hi:[0,1]
	v_pk_mul_f32 v[130:131], v[124:125], v[124:125]
	v_cndmask_b32_e32 v128, v198, v128, vcc
	v_lshlrev_b32_e32 v201, 2, v128
	v_xor_b32_e32 v128, 32, v198
	v_cmp_lt_i32_e32 vcc, v128, v129
	s_nop 1
	v_cndmask_b32_e32 v128, v198, v128, vcc
	v_lshlrev_b32_e32 v202, 2, v128
	v_add_u32_e32 v128, 16, v184
	v_and_b32_e32 v204, 63, v128
	v_add_u32_e32 v128, 48, v184
	v_and_b32_e32 v200, 63, v128
	v_bfe_u32 v220, v150, 6, 6
	v_lshl_add_u32 v220, v220, 5, v151
	v_ashrrev_i32_e32 v221, 31, v220
	v_lshl_add_u64 v[220:221], v[220:221], 2, s[58:59]
	global_load_dwordx4 v[222:225], v[220:221], off
	global_load_dwordx4 v[226:229], v[220:221], off offset:16
	v_lshl_add_u32 v220, v205, 5, v151
	v_ashrrev_i32_e32 v221, 31, v220
	v_lshl_add_u64 v[220:221], v[220:221], 2, s[58:59]
	global_load_dwordx4 v[230:233], v[220:221], off
	global_load_dwordx4 v[234:237], v[220:221], off offset:16
	v_add_u32_e32 v220, 0x10, v150
	v_bfe_u32 v220, v220, 6, 6
	v_lshl_add_u32 v220, v220, 5, v151
	v_ashrrev_i32_e32 v221, 31, v220
	v_lshl_add_u64 v[220:221], v[220:221], 2, s[58:59]
	global_load_dwordx4 v[238:241], v[220:221], off
	global_load_dwordx4 v[242:245], v[220:221], off offset:16
	v_lshl_add_u32 v220, v204, 5, v151
	v_ashrrev_i32_e32 v221, 31, v220
	v_lshl_add_u64 v[220:221], v[220:221], 2, s[58:59]
	global_load_dwordx4 v[246:249], v[220:221], off
	global_load_dwordx4 v[250:253], v[220:221], off offset:16
	v_pk_mul_f32 v[128:129], v[126:127], v[126:127]
	s_nop 0
	v_pk_mov_b32 v[132:133], v[130:131], v[128:129] op_sel:[1,0]
	v_mov_b32_e32 v131, v129
	v_pk_add_f32 v[128:129], v[132:133], v[130:131]
	v_pk_mul_f32 v[130:131], v[122:123], v[122:123]
	v_pk_mul_f32 v[132:133], v[120:121], v[120:121]
	v_pk_add_f32 v[128:129], v[128:129], v[128:129] op_sel:[0,1] op_sel_hi:[1,0]
	s_waitcnt lgkmcnt(0)
	v_pk_mov_b32 v[134:135], v[132:133], v[130:131] op_sel:[1,0]
	v_mov_b32_e32 v133, v131
	v_pk_add_f32 v[130:131], v[134:135], v[132:133]
	v_mul_f32_e32 v132, v112, v112
	v_mul_f32_e32 v133, v113, v113
	v_pk_add_f32 v[130:131], v[130:131], v[130:131] op_sel:[0,1] op_sel_hi:[1,0]
	v_mov_b32_e32 v129, v132
	v_mov_b32_e32 v131, v133
	v_pk_add_f32 v[128:129], v[128:129], v[130:131]
	v_mul_f32_e32 v130, v117, v117
	v_mul_f32_e32 v132, v119, v119
	v_mul_f32_e32 v134, v114, v114
	v_mul_f32_e32 v135, v115, v115
	v_pk_fma_f32 v[130:131], v[116:117], v[116:117], v[130:131] op_sel_hi:[1,1,0]
	v_pk_fma_f32 v[132:133], v[118:119], v[118:119], v[132:133] op_sel_hi:[1,1,0]
	v_mov_b32_e32 v131, v134
	v_mov_b32_e32 v133, v135
	v_pk_add_f32 v[130:131], v[130:131], v[132:133]
	s_nop 0
	v_pk_add_f32 v[128:129], v[128:129], v[130:131]
	s_nop 0
	v_add_f32_e32 v128, v128, v129
	ds_bpermute_b32 v129, v201, v128
	s_waitcnt lgkmcnt(0)
	v_add_f32_e32 v128, v128, v129
	ds_bpermute_b32 v129, v202, v128
	s_waitcnt lgkmcnt(0)
	v_add_f32_e32 v128, v128, v129
	v_fmamk_f32 v128, v128, 0x3c800000, v196
	v_cmp_gt_f32_e32 vcc, s49, v128
	v_mul_f32_e32 v129, 0x4f800000, v128
	s_nop 0
	v_cndmask_b32_e32 v128, v128, v129, vcc
	v_sqrt_f32_e32 v129, v128
	s_nop 0
	v_add_u32_e32 v130, -1, v129
	v_fma_f32 v131, -v130, v129, v128
	v_cmp_ge_f32_e64 s[0:1], 0, v131
	v_add_u32_e32 v131, 1, v129
	s_nop 0
	v_cndmask_b32_e64 v130, v129, v130, s[0:1]
	v_fma_f32 v129, -v131, v129, v128
	v_cmp_lt_f32_e64 s[0:1], 0, v129
	s_nop 1
	v_cndmask_b32_e64 v129, v130, v131, s[0:1]
	v_mul_f32_e32 v130, 0x37800000, v129
	v_cndmask_b32_e32 v129, v129, v130, vcc
	v_cmp_class_f32_e32 vcc, v128, v197
	s_nop 1
	v_cndmask_b32_e32 v128, v129, v128, vcc
	v_div_scale_f32 v129, s[0:1], v128, v128, 1.0
	v_rcp_f32_e32 v130, v129
	s_nop 0
	v_fma_f32 v131, -v129, v130, 1.0
	v_fmac_f32_e32 v130, v131, v130
	v_div_scale_f32 v131, vcc, 1.0, v128, 1.0
	v_mul_f32_e32 v132, v131, v130
	v_fma_f32 v133, -v129, v132, v131
	v_fmac_f32_e32 v132, v133, v130
	v_fma_f32 v129, -v129, v132, v131
	v_div_fmas_f32 v129, v129, v130, v132
	v_div_fixup_f32 v140, v129, v128, 1.0
	v_ashrrev_i32_e32 v128, 11, v150
	v_and_b32_e32 v128, -2, v128
	v_add_u32_e32 v128, s69, v128
	v_bfe_u32 v132, v150, 6, 6
	v_ashrrev_i32_e32 v129, 31, v128
	v_lshlrev_b64 v[128:129], 12, v[128:129]
	v_lshlrev_b32_e32 v130, 6, v132
	v_or3_b32 v128, v128, v130, v205
	v_lshlrev_b64 v[170:171], 7, v[128:129]
	v_mad_i64_i32 v[128:129], s[0:1], s6, v150, 0
	v_lshl_add_u64 v[172:173], v[128:129], 1, s[10:11]
	v_pk_mul_f32 v[128:129], v[126:127], v[140:141] op_sel_hi:[1,0]
	v_pk_mul_f32 v[130:131], v[124:125], v[140:141] op_sel_hi:[1,0]
	v_pk_mul_f32 v[176:177], v[160:161], v[128:129]
	v_pk_mul_f32 v[128:129], v[120:121], v[140:141] op_sel_hi:[1,0]
	v_pk_mul_f32 v[174:175], v[162:163], v[130:131]
	v_pk_mul_f32 v[180:181], v[166:167], v[128:129]
	v_lshl_add_u32 v128, v132, 5, v151
	v_ashrrev_i32_e32 v129, 31, v128
	v_pk_mul_f32 v[130:131], v[122:123], v[140:141] op_sel_hi:[1,0]
	v_lshl_add_u64 v[132:133], v[128:129], 2, s[58:59]
	v_pk_mul_f32 v[178:179], v[164:165], v[130:131]
	s_waitcnt vmcnt(6)
; __device__ __forceinline__ float quad_sum(float s) { s += __shfl_xor(s, 16); s += __shfl_xor(s, 32); return s; }
; __device__ __forceinline__ void st4(bf16_t* p, f32x4 v) { u32x2 w; w.x = cvt_pk_bf16(v[0], v[1]); w.y = cvt_pk_bf16(v[2], v[3]); *(u32x2*)p = w; }
;     __device__ __forceinline__ void operator()(const f32x4 (&acc)[2][2][4][2], const Unit& u, int wr, int wc, int fr, int fq) const {
;     ...
;                     s = quad_sum(s); const float rstd = 1.0f / sqrtf(s * (1.f / 64.f) + NEPS);
;                     const int srow = row & (SEQL - 1), prow = srow >> 6, pcol = srow & 63;
; #pragma unroll
;                     for (int bj = 0; bj < 2; ++bj) { const int pos = bj ? pcol : prow; f32x4 y1, y2;
;                         rope4(acc[ai][bj][m][0] * rstd * gv[bj][0], acc[ai][bj][m][1] * rstd * gv[bj][1], ropeG + (pos * 16 + 4 * fq) * 2, y1, y2);
;                         bf16_t* dp = isq ? dst + (size_t)row * pitch : KG + ((((size_t)((row >> 12) * 2 + wc) * 64 + (srow >> 6)) * 64 + (srow & 63)) * 64);
;                         st4(dp + 32 * bj + 4 * fq, y1); st4(dp + 32 * bj + 16 + 4 * fq, y2); } }
	v_mov_b32_e32 v128, v222
	v_mov_b32_e32 v129, v223
	v_mov_b32_e32 v130, v224
	v_mov_b32_e32 v131, v225
	s_nop 0
	v_mov_b32_e32 v132, v226
	v_mov_b32_e32 v133, v227
	v_mov_b32_e32 v134, v228
	v_mov_b32_e32 v135, v229
	v_lshl_add_u64 v[170:171], s[42:43], 0, v[170:171]
	v_cndmask_b32_e64 v171, v171, v173, s[92:93]
	v_cndmask_b32_e64 v170, v170, v172, s[92:93]
	v_lshl_add_u64 v[170:171], v[170:171], 0, v[168:169]
	v_mov_b32_e32 v182, v129
	v_mov_b32_e32 v183, v131
	v_mov_b32_e32 v206, v133
	v_mov_b32_e32 v207, v135
	v_pk_mul_f32 v[184:185], v[182:183], v[180:181]
	v_pk_mul_f32 v[208:209], v[206:207], v[178:179]
	v_mov_b32_e32 v133, v134
	v_mov_b32_e32 v129, v130
	v_pk_fma_f32 v[134:135], v[132:133], v[176:177], v[208:209] neg_lo:[0,0,1] neg_hi:[0,0,1]
	v_pk_fma_f32 v[130:131], v[128:129], v[174:175], v[184:185] neg_lo:[0,0,1] neg_hi:[0,0,1]
	v_pk_mul_f32 v[128:129], v[128:129], v[180:181]
	v_pk_mul_f32 v[132:133], v[132:133], v[178:179]
	v_pk_fma_f32 v[128:129], v[182:183], v[174:175], v[128:129]
	v_pk_fma_f32 v[132:133], v[206:207], v[176:177], v[132:133]
	v_cvt_pk_bf16_f32 v128, v128, v129
	v_cvt_pk_bf16_f32 v129, v132, v133
	global_store_dwordx2 v[170:171], v[128:129], off offset:32
	v_pk_mul_f32 v[128:129], v[118:119], v[140:141] op_sel_hi:[1,0]
	v_cvt_pk_bf16_f32 v130, v130, v131
	v_pk_mul_f32 v[176:177], v[152:153], v[128:129]
	v_pk_mul_f32 v[128:129], v[112:113], v[140:141] op_sel_hi:[1,0]
	v_cvt_pk_bf16_f32 v131, v134, v135
	v_pk_mul_f32 v[180:181], v[156:157], v[128:129]
	v_lshl_add_u32 v128, v205, 5, v151
	global_store_dwordx2 v[170:171], v[130:131], off
	v_pk_mul_f32 v[130:131], v[116:117], v[140:141] op_sel_hi:[1,0]
	v_ashrrev_i32_e32 v129, 31, v128
	v_pk_mul_f32 v[174:175], v[158:159], v[130:131]
	v_pk_mul_f32 v[130:131], v[114:115], v[140:141] op_sel_hi:[1,0]
	v_lshl_add_u64 v[172:173], v[128:129], 2, s[58:59]
	v_pk_mul_f32 v[178:179], v[154:155], v[130:131]
	s_waitcnt vmcnt(6)
	v_mov_b32_e32 v128, v230
	v_mov_b32_e32 v129, v231
	v_mov_b32_e32 v130, v232
	v_mov_b32_e32 v131, v233
	v_mov_b32_e32 v132, v234
	v_mov_b32_e32 v133, v235
	v_mov_b32_e32 v134, v236
	v_mov_b32_e32 v135, v237
	v_mov_b32_e32 v182, v129
	v_mov_b32_e32 v183, v131
	v_mov_b32_e32 v206, v133
	v_mov_b32_e32 v207, v135
	v_pk_mul_f32 v[184:185], v[182:183], v[180:181]
	v_pk_mul_f32 v[208:209], v[206:207], v[178:179]
	v_mov_b32_e32 v133, v134
	v_mov_b32_e32 v129, v130
	v_pk_fma_f32 v[134:135], v[132:133], v[176:177], v[208:209] neg_lo:[0,0,1] neg_hi:[0,0,1]
	v_pk_fma_f32 v[130:131], v[128:129], v[174:175], v[184:185] neg_lo:[0,0,1] neg_hi:[0,0,1]
	v_pk_mul_f32 v[128:129], v[128:129], v[180:181]
	v_pk_mul_f32 v[132:133], v[132:133], v[178:179]
	v_pk_fma_f32 v[128:129], v[182:183], v[174:175], v[128:129]
	v_pk_fma_f32 v[132:133], v[206:207], v[176:177], v[132:133]
	v_cvt_pk_bf16_f32 v130, v130, v131
	v_cvt_pk_bf16_f32 v131, v134, v135
	v_cvt_pk_bf16_f32 v128, v128, v129
	v_cvt_pk_bf16_f32 v129, v132, v133
	global_store_dwordx2 v[170:171], v[130:131], off offset:64
	global_store_dwordx2 v[170:171], v[128:129], off offset:96
	v_add_u32_e32 v220, 0x20, v150
	v_bfe_u32 v220, v220, 6, 6
	v_lshl_add_u32 v220, v220, 5, v151
	v_ashrrev_i32_e32 v221, 31, v220
	v_lshl_add_u64 v[220:221], v[220:221], 2, s[58:59]
	global_load_dwordx4 v[222:225], v[220:221], off
	global_load_dwordx4 v[226:229], v[220:221], off offset:16
	v_lshl_add_u32 v220, v203, 5, v151
	v_ashrrev_i32_e32 v221, 31, v220
	v_lshl_add_u64 v[220:221], v[220:221], 2, s[58:59]
	global_load_dwordx4 v[230:233], v[220:221], off
	global_load_dwordx4 v[234:237], v[220:221], off offset:16
	v_pk_mul_f32 v[128:129], v[110:111], v[110:111]
	v_pk_mul_f32 v[130:131], v[108:109], v[108:109]
	s_nop 0
	v_pk_mov_b32 v[132:133], v[130:131], v[128:129] op_sel:[1,0]
	v_mov_b32_e32 v131, v129
	v_pk_add_f32 v[128:129], v[132:133], v[130:131]
	v_pk_mul_f32 v[130:131], v[106:107], v[106:107]
	v_pk_mul_f32 v[132:133], v[104:105], v[104:105]
	v_pk_add_f32 v[128:129], v[128:129], v[128:129] op_sel:[0,1] op_sel_hi:[1,0]
	v_pk_mov_b32 v[134:135], v[132:133], v[130:131] op_sel:[1,0]
	v_mov_b32_e32 v133, v131
	v_pk_add_f32 v[130:131], v[134:135], v[132:133]
	v_mul_f32_e32 v132, v96, v96
	v_mul_f32_e32 v133, v97, v97
	v_pk_add_f32 v[130:131], v[130:131], v[130:131] op_sel:[0,1] op_sel_hi:[1,0]
	v_mov_b32_e32 v129, v132
	v_mov_b32_e32 v131, v133
	v_pk_add_f32 v[128:129], v[128:129], v[130:131]
	v_mul_f32_e32 v130, v101, v101
	v_mul_f32_e32 v132, v103, v103
	v_mul_f32_e32 v134, v98, v98
	v_mul_f32_e32 v135, v99, v99
	v_pk_fma_f32 v[130:131], v[100:101], v[100:101], v[130:131] op_sel_hi:[1,1,0]
	v_pk_fma_f32 v[132:133], v[102:103], v[102:103], v[132:133] op_sel_hi:[1,1,0]
	v_mov_b32_e32 v131, v134
	v_mov_b32_e32 v133, v135
	v_pk_add_f32 v[130:131], v[130:131], v[132:133]
	s_nop 0
	v_pk_add_f32 v[128:129], v[128:129], v[130:131]
	v_add_u32_e32 v130, 16, v150
	v_add_f32_e32 v128, v128, v129
	ds_bpermute_b32 v129, v201, v128
	s_waitcnt lgkmcnt(0)
	v_add_f32_e32 v128, v128, v129
	ds_bpermute_b32 v129, v202, v128
	s_waitcnt lgkmcnt(0)
; __device__ __forceinline__ float dot4(f32x4 v) { return (v[0] * v[0] + v[1] * v[1]) + (v[2] * v[2] + v[3] * v[3]); }
; __device__ __forceinline__ float quad_sum(float s) { s += __shfl_xor(s, 16); s += __shfl_xor(s, 32); return s; }
; __device__ __forceinline__ void st4(bf16_t* p, f32x4 v) { u32x2 w; w.x = cvt_pk_bf16(v[0], v[1]); w.y = cvt_pk_bf16(v[2], v[3]); *(u32x2*)p = w; }
;     __device__ __forceinline__ void operator()(const f32x4 (&acc)[2][2][4][2], const Unit& u, int wr, int wc, int fr, int fq) const {
;     ...
;                 for (int m = 0; m < 4; ++m) { const int row = row0 + ai * HALF + m * 16; float s = 0.f;
; #pragma unroll
;                     for (int bj = 0; bj < 2; ++bj)
; #pragma unroll
;                         for (int n = 0; n < 2; ++n) s += dot4(acc[ai][bj][m][n]);
;                     s = quad_sum(s); const float rstd = 1.0f / sqrtf(s * (1.f / 64.f) + NEPS);
;                     const int srow = row & (SEQL - 1), prow = srow >> 6, pcol = srow & 63;
; #pragma unroll
;                     for (int bj = 0; bj < 2; ++bj) { const int pos = bj ? pcol : prow; f32x4 y1, y2;
;                         rope4(acc[ai][bj][m][0] * rstd * gv[bj][0], acc[ai][bj][m][1] * rstd * gv[bj][1], ropeG + (pos * 16 + 4 * fq) * 2, y1, y2);
;                         bf16_t* dp = isq ? dst + (size_t)row * pitch : KG + ((((size_t)((row >> 12) * 2 + wc) * 64 + (srow >> 6)) * 64 + (srow & 63)) * 64);
;                         st4(dp + 32 * bj + 4 * fq, y1); st4(dp + 32 * bj + 16 + 4 * fq, y2); } }
	v_add_f32_e32 v128, v128, v129
	v_fmamk_f32 v128, v128, 0x3c800000, v196
	v_cmp_gt_f32_e32 vcc, s49, v128
	v_mul_f32_e32 v129, 0x4f800000, v128
	s_nop 0
	v_cndmask_b32_e32 v128, v128, v129, vcc
	v_sqrt_f32_e32 v129, v128
	s_nop 0
	v_add_u32_e32 v131, -1, v129
	v_fma_f32 v132, -v131, v129, v128
	v_cmp_ge_f32_e64 s[0:1], 0, v132
	v_add_u32_e32 v132, 1, v129
	s_nop 0
	v_cndmask_b32_e64 v131, v129, v131, s[0:1]
	v_fma_f32 v129, -v132, v129, v128
	v_cmp_lt_f32_e64 s[0:1], 0, v129
	s_nop 1
	v_cndmask_b32_e64 v129, v131, v132, s[0:1]
	v_mul_f32_e32 v131, 0x37800000, v129
	v_cndmask_b32_e32 v129, v129, v131, vcc
	v_cmp_class_f32_e32 vcc, v128, v197
	s_nop 1
	v_cndmask_b32_e32 v128, v129, v128, vcc
	v_div_scale_f32 v129, s[0:1], v128, v128, 1.0
	v_rcp_f32_e32 v131, v129
	s_nop 0
	v_fma_f32 v132, -v129, v131, 1.0
	v_fmac_f32_e32 v131, v132, v131
	v_div_scale_f32 v132, vcc, 1.0, v128, 1.0
	v_mul_f32_e32 v133, v132, v131
	v_fma_f32 v134, -v129, v133, v132
	v_fmac_f32_e32 v133, v134, v131
	v_fma_f32 v129, -v129, v133, v132
	v_div_fmas_f32 v129, v129, v131, v133
	v_div_fixup_f32 v140, v129, v128, 1.0
	v_ashrrev_i32_e32 v128, 11, v130
	v_and_b32_e32 v128, -2, v128
	v_add_u32_e32 v128, s69, v128
	v_bfe_u32 v132, v130, 6, 6
	v_ashrrev_i32_e32 v129, 31, v128
	v_lshlrev_b64 v[128:129], 12, v[128:129]
	v_lshlrev_b32_e32 v131, 6, v132
	v_or3_b32 v128, v128, v131, v204
	v_lshlrev_b64 v[170:171], 7, v[128:129]
	v_mad_i64_i32 v[128:129], s[0:1], s6, v130, 0
	v_lshl_add_u64 v[174:175], v[128:129], 1, s[10:11]
	v_pk_mul_f32 v[128:129], v[110:111], v[140:141] op_sel_hi:[1,0]
	v_pk_mul_f32 v[130:131], v[108:109], v[140:141] op_sel_hi:[1,0]
	v_pk_mul_f32 v[178:179], v[160:161], v[128:129]
	v_pk_mul_f32 v[128:129], v[104:105], v[140:141] op_sel_hi:[1,0]
	v_pk_mul_f32 v[176:177], v[162:163], v[130:131]
	v_pk_mul_f32 v[182:183], v[166:167], v[128:129]
	v_lshl_add_u32 v128, v132, 5, v151
	v_ashrrev_i32_e32 v129, 31, v128
	v_pk_mul_f32 v[130:131], v[106:107], v[140:141] op_sel_hi:[1,0]
	v_lshl_add_u64 v[132:133], v[128:129], 2, s[58:59]
	v_pk_mul_f32 v[180:181], v[164:165], v[130:131]
	s_waitcnt vmcnt(10)
	v_mov_b32_e32 v128, v238
	v_mov_b32_e32 v129, v239
	v_mov_b32_e32 v130, v240
	v_mov_b32_e32 v131, v241
	s_nop 0
	v_mov_b32_e32 v132, v242
	v_mov_b32_e32 v133, v243
	v_mov_b32_e32 v134, v244
	v_mov_b32_e32 v135, v245
	v_lshl_add_u64 v[170:171], s[42:43], 0, v[170:171]
	v_cndmask_b32_e64 v171, v171, v175, s[92:93]
	v_cndmask_b32_e64 v170, v170, v174, s[92:93]
	v_lshl_add_u64 v[174:175], v[170:171], 0, v[168:169]
	v_mov_b32_e32 v184, v129
	v_mov_b32_e32 v185, v131
	v_mov_b32_e32 v208, v133
	v_mov_b32_e32 v209, v135
	v_pk_mul_f32 v[206:207], v[184:185], v[182:183]
	v_pk_mul_f32 v[210:211], v[208:209], v[180:181]
	v_mov_b32_e32 v133, v134
	v_mov_b32_e32 v129, v130
	v_pk_fma_f32 v[134:135], v[132:133], v[178:179], v[210:211] neg_lo:[0,0,1] neg_hi:[0,0,1]
	v_pk_fma_f32 v[130:131], v[128:129], v[176:177], v[206:207] neg_lo:[0,0,1] neg_hi:[0,0,1]
	v_pk_mul_f32 v[128:129], v[128:129], v[182:183]
	v_pk_mul_f32 v[132:133], v[132:133], v[180:181]
	v_pk_fma_f32 v[128:129], v[184:185], v[176:177], v[128:129]
	v_pk_fma_f32 v[132:133], v[208:209], v[178:179], v[132:133]
	v_cvt_pk_bf16_f32 v128, v128, v129
	v_cvt_pk_bf16_f32 v129, v132, v133
	global_store_dwordx2 v[174:175], v[128:129], off offset:32
	v_pk_mul_f32 v[128:129], v[102:103], v[140:141] op_sel_hi:[1,0]
	v_cvt_pk_bf16_f32 v130, v130, v131
	v_pk_mul_f32 v[178:179], v[152:153], v[128:129]
	v_pk_mul_f32 v[128:129], v[96:97], v[140:141] op_sel_hi:[1,0]
	v_cvt_pk_bf16_f32 v131, v134, v135
	v_pk_mul_f32 v[182:183], v[156:157], v[128:129]
	v_lshl_add_u32 v128, v204, 5, v151
	global_store_dwordx2 v[174:175], v[130:131], off
	v_pk_mul_f32 v[130:131], v[100:101], v[140:141] op_sel_hi:[1,0]
	v_ashrrev_i32_e32 v129, 31, v128
	v_pk_mul_f32 v[176:177], v[158:159], v[130:131]
	v_pk_mul_f32 v[130:131], v[98:99], v[140:141] op_sel_hi:[1,0]
	v_lshl_add_u64 v[170:171], v[128:129], 2, s[58:59]
	v_pk_mul_f32 v[180:181], v[154:155], v[130:131]
	s_waitcnt vmcnt(10)
	v_mov_b32_e32 v128, v246
	v_mov_b32_e32 v129, v247
	v_mov_b32_e32 v130, v248
	v_mov_b32_e32 v131, v249
	v_mov_b32_e32 v132, v250
	v_mov_b32_e32 v133, v251
	v_mov_b32_e32 v134, v252
	v_mov_b32_e32 v135, v253
	v_mov_b32_e32 v184, v129
	v_mov_b32_e32 v185, v131
	v_mov_b32_e32 v208, v133
	v_mov_b32_e32 v209, v135
	v_pk_mul_f32 v[206:207], v[184:185], v[182:183]
	v_pk_mul_f32 v[210:211], v[208:209], v[180:181]
	v_mov_b32_e32 v133, v134
	v_mov_b32_e32 v129, v130
	v_pk_fma_f32 v[134:135], v[132:133], v[178:179], v[210:211] neg_lo:[0,0,1] neg_hi:[0,0,1]
	v_pk_fma_f32 v[130:131], v[128:129], v[176:177], v[206:207] neg_lo:[0,0,1] neg_hi:[0,0,1]
	v_pk_mul_f32 v[128:129], v[128:129], v[182:183]
	v_pk_mul_f32 v[132:133], v[132:133], v[180:181]
	v_pk_fma_f32 v[128:129], v[184:185], v[176:177], v[128:129]
	v_pk_fma_f32 v[132:133], v[208:209], v[178:179], v[132:133]
	v_cvt_pk_bf16_f32 v130, v130, v131
	v_cvt_pk_bf16_f32 v131, v134, v135
	v_cvt_pk_bf16_f32 v128, v128, v129
	v_cvt_pk_bf16_f32 v129, v132, v133
	global_store_dwordx2 v[174:175], v[130:131], off offset:64
	global_store_dwordx2 v[174:175], v[128:129], off offset:96
	v_add_u32_e32 v220, 0x30, v150
	v_bfe_u32 v220, v220, 6, 6
	v_lshl_add_u32 v220, v220, 5, v151
	v_ashrrev_i32_e32 v221, 31, v220
	v_lshl_add_u64 v[220:221], v[220:221], 2, s[58:59]
	global_load_dwordx4 v[238:241], v[220:221], off
	global_load_dwordx4 v[242:245], v[220:221], off offset:16
	v_lshl_add_u32 v220, v200, 5, v151
	v_ashrrev_i32_e32 v221, 31, v220
	v_lshl_add_u64 v[220:221], v[220:221], 2, s[58:59]
	global_load_dwordx4 v[246:249], v[220:221], off
	global_load_dwordx4 v[250:253], v[220:221], off offset:16
	v_pk_mul_f32 v[128:129], v[94:95], v[94:95]
	v_pk_mul_f32 v[130:131], v[92:93], v[92:93]
	s_nop 0
	v_pk_mov_b32 v[132:133], v[130:131], v[128:129] op_sel:[1,0]
	v_mov_b32_e32 v131, v129
	v_pk_add_f32 v[128:129], v[132:133], v[130:131]
	v_pk_mul_f32 v[130:131], v[90:91], v[90:91]
	v_pk_mul_f32 v[132:133], v[88:89], v[88:89]
	v_pk_add_f32 v[128:129], v[128:129], v[128:129] op_sel:[0,1] op_sel_hi:[1,0]
	v_pk_mov_b32 v[134:135], v[132:133], v[130:131] op_sel:[1,0]
	v_mov_b32_e32 v133, v131
	v_pk_add_f32 v[130:131], v[134:135], v[132:133]
	v_mul_f32_e32 v132, v80, v80
	v_mul_f32_e32 v133, v81, v81
	v_pk_add_f32 v[130:131], v[130:131], v[130:131] op_sel:[0,1] op_sel_hi:[1,0]
	v_mov_b32_e32 v129, v132
	v_mov_b32_e32 v131, v133
	v_pk_add_f32 v[128:129], v[128:129], v[130:131]
	v_mul_f32_e32 v130, v85, v85
	v_mul_f32_e32 v132, v87, v87
	v_mul_f32_e32 v134, v82, v82
	v_mul_f32_e32 v135, v83, v83
	v_pk_fma_f32 v[130:131], v[84:85], v[84:85], v[130:131] op_sel_hi:[1,1,0]
	v_pk_fma_f32 v[132:133], v[86:87], v[86:87], v[132:133] op_sel_hi:[1,1,0]
	v_mov_b32_e32 v131, v134
	v_mov_b32_e32 v133, v135
	v_pk_add_f32 v[130:131], v[130:131], v[132:133]
	s_nop 0
	v_pk_add_f32 v[128:129], v[128:129], v[130:131]
	v_add_u32_e32 v130, 32, v150
	v_add_f32_e32 v128, v128, v129
	ds_bpermute_b32 v129, v201, v128
	s_waitcnt lgkmcnt(0)
; __device__ __forceinline__ float dot4(f32x4 v) { return (v[0] * v[0] + v[1] * v[1]) + (v[2] * v[2] + v[3] * v[3]); }
; __device__ __forceinline__ float quad_sum(float s) { s += __shfl_xor(s, 16); s += __shfl_xor(s, 32); return s; }
; __device__ __forceinline__ void st4(bf16_t* p, f32x4 v) { u32x2 w; w.x = cvt_pk_bf16(v[0], v[1]); w.y = cvt_pk_bf16(v[2], v[3]); *(u32x2*)p = w; }
;     __device__ __forceinline__ void operator()(const f32x4 (&acc)[2][2][4][2], const Unit& u, int wr, int wc, int fr, int fq) const {
;     ...
;                 for (int m = 0; m < 4; ++m) { const int row = row0 + ai * HALF + m * 16; float s = 0.f;
; #pragma unroll
;                     for (int bj = 0; bj < 2; ++bj)
; #pragma unroll
;                         for (int n = 0; n < 2; ++n) s += dot4(acc[ai][bj][m][n]);
;                     s = quad_sum(s); const float rstd = 1.0f / sqrtf(s * (1.f / 64.f) + NEPS);
;                     const int srow = row & (SEQL - 1), prow = srow >> 6, pcol = srow & 63;
; #pragma unroll
;                     for (int bj = 0; bj < 2; ++bj) { const int pos = bj ? pcol : prow; f32x4 y1, y2;
;                         rope4(acc[ai][bj][m][0] * rstd * gv[bj][0], acc[ai][bj][m][1] * rstd * gv[bj][1], ropeG + (pos * 16 + 4 * fq) * 2, y1, y2);
;                         bf16_t* dp = isq ? dst + (size_t)row * pitch : KG + ((((size_t)((row >> 12) * 2 + wc) * 64 + (srow >> 6)) * 64 + (srow & 63)) * 64);
;                         st4(dp + 32 * bj + 4 * fq, y1); st4(dp + 32 * bj + 16 + 4 * fq, y2); } }
	v_add_f32_e32 v128, v128, v129
	ds_bpermute_b32 v129, v202, v128
	s_waitcnt lgkmcnt(0)
	v_add_f32_e32 v128, v128, v129
	v_fmamk_f32 v128, v128, 0x3c800000, v196
	v_cmp_gt_f32_e32 vcc, s49, v128
	v_mul_f32_e32 v129, 0x4f800000, v128
	s_nop 0
	v_cndmask_b32_e32 v128, v128, v129, vcc
	v_sqrt_f32_e32 v129, v128
	s_nop 0
	v_add_u32_e32 v131, -1, v129
	v_fma_f32 v132, -v131, v129, v128
	v_cmp_ge_f32_e64 s[0:1], 0, v132
	v_add_u32_e32 v132, 1, v129
	s_nop 0
	v_cndmask_b32_e64 v131, v129, v131, s[0:1]
	v_fma_f32 v129, -v132, v129, v128
	v_cmp_lt_f32_e64 s[0:1], 0, v129
	s_nop 1
	v_cndmask_b32_e64 v129, v131, v132, s[0:1]
	v_mul_f32_e32 v131, 0x37800000, v129
	v_cndmask_b32_e32 v129, v129, v131, vcc
	v_cmp_class_f32_e32 vcc, v128, v197
	s_nop 1
	v_cndmask_b32_e32 v128, v129, v128, vcc
	v_div_scale_f32 v129, s[0:1], v128, v128, 1.0
	v_rcp_f32_e32 v131, v129
	s_nop 0
	v_fma_f32 v132, -v129, v131, 1.0
	v_fmac_f32_e32 v131, v132, v131
	v_div_scale_f32 v132, vcc, 1.0, v128, 1.0
	v_mul_f32_e32 v133, v132, v131
	v_fma_f32 v134, -v129, v133, v132
	v_fmac_f32_e32 v133, v134, v131
	v_fma_f32 v129, -v129, v133, v132
	v_div_fmas_f32 v129, v129, v131, v133
	v_div_fixup_f32 v140, v129, v128, 1.0
	v_ashrrev_i32_e32 v128, 11, v130
	v_and_b32_e32 v128, -2, v128
	v_add_u32_e32 v128, s69, v128
	v_bfe_u32 v132, v130, 6, 6
	v_ashrrev_i32_e32 v129, 31, v128
	v_lshlrev_b64 v[128:129], 12, v[128:129]
	v_lshlrev_b32_e32 v131, 6, v132
	v_or3_b32 v128, v128, v131, v203
	v_lshlrev_b64 v[174:175], 7, v[128:129]
	v_mad_i64_i32 v[128:129], s[0:1], s6, v130, 0
	v_lshl_add_u64 v[176:177], v[128:129], 1, s[10:11]
	v_pk_mul_f32 v[128:129], v[94:95], v[140:141] op_sel_hi:[1,0]
	v_pk_mul_f32 v[130:131], v[92:93], v[140:141] op_sel_hi:[1,0]
	v_pk_mul_f32 v[180:181], v[160:161], v[128:129]
	v_pk_mul_f32 v[128:129], v[88:89], v[140:141] op_sel_hi:[1,0]
	v_pk_mul_f32 v[178:179], v[162:163], v[130:131]
	v_pk_mul_f32 v[184:185], v[166:167], v[128:129]
	v_lshl_add_u32 v128, v132, 5, v151
	v_ashrrev_i32_e32 v129, 31, v128
	v_pk_mul_f32 v[130:131], v[90:91], v[140:141] op_sel_hi:[1,0]
	v_lshl_add_u64 v[132:133], v[128:129], 2, s[58:59]
	v_pk_mul_f32 v[182:183], v[164:165], v[130:131]
	s_waitcnt vmcnt(10)
	v_mov_b32_e32 v128, v222
	v_mov_b32_e32 v129, v223
	v_mov_b32_e32 v130, v224
	v_mov_b32_e32 v131, v225
	s_nop 0
	v_mov_b32_e32 v132, v226
	v_mov_b32_e32 v133, v227
	v_mov_b32_e32 v134, v228
	v_mov_b32_e32 v135, v229
	v_lshl_add_u64 v[174:175], s[42:43], 0, v[174:175]
	v_cndmask_b32_e64 v175, v175, v177, s[92:93]
	v_cndmask_b32_e64 v174, v174, v176, s[92:93]
	v_mov_b32_e32 v206, v129
	v_mov_b32_e32 v207, v131
	v_mov_b32_e32 v210, v133
	v_mov_b32_e32 v211, v135
	v_pk_mul_f32 v[208:209], v[206:207], v[184:185]
	v_pk_mul_f32 v[212:213], v[210:211], v[182:183]
	v_mov_b32_e32 v133, v134
	v_mov_b32_e32 v129, v130
	v_pk_fma_f32 v[134:135], v[132:133], v[180:181], v[212:213] neg_lo:[0,0,1] neg_hi:[0,0,1]
	v_pk_fma_f32 v[130:131], v[128:129], v[178:179], v[208:209] neg_lo:[0,0,1] neg_hi:[0,0,1]
	v_pk_mul_f32 v[128:129], v[128:129], v[184:185]
	v_cvt_pk_bf16_f32 v130, v130, v131
	v_pk_fma_f32 v[128:129], v[206:207], v[178:179], v[128:129]
	v_lshl_add_u64 v[178:179], v[174:175], 0, v[168:169]
	v_cvt_pk_bf16_f32 v131, v134, v135
	v_pk_mul_f32 v[132:133], v[132:133], v[182:183]
	global_store_dwordx2 v[178:179], v[130:131], off
	v_pk_mul_f32 v[130:131], v[84:85], v[140:141] op_sel_hi:[1,0]
	v_pk_fma_f32 v[132:133], v[210:211], v[180:181], v[132:133]
	v_pk_mul_f32 v[180:181], v[158:159], v[130:131]
	v_pk_mul_f32 v[130:131], v[80:81], v[140:141] op_sel_hi:[1,0]
	v_cvt_pk_bf16_f32 v128, v128, v129
	v_pk_mul_f32 v[184:185], v[156:157], v[130:131]
	v_lshl_add_u32 v130, v203, 5, v151
	v_cvt_pk_bf16_f32 v129, v132, v133
	v_ashrrev_i32_e32 v131, 31, v130
	global_store_dwordx2 v[178:179], v[128:129], off offset:32
	v_pk_mul_f32 v[132:133], v[82:83], v[140:141] op_sel_hi:[1,0]
	v_lshl_add_u64 v[130:131], v[130:131], 2, s[58:59]
	v_pk_mul_f32 v[182:183], v[154:155], v[132:133]
	s_waitcnt vmcnt(10)
	v_mov_b32_e32 v132, v230
	v_mov_b32_e32 v133, v231
	v_mov_b32_e32 v134, v232
	v_mov_b32_e32 v135, v233
	v_mov_b32_e32 v174, v234
	v_mov_b32_e32 v175, v235
	v_mov_b32_e32 v176, v236
	v_mov_b32_e32 v177, v237
	v_pk_mul_f32 v[128:129], v[86:87], v[140:141] op_sel_hi:[1,0]
	v_mul_f32_e32 v140, v66, v66
	v_pk_mul_f32 v[128:129], v[152:153], v[128:129]
	v_mov_b32_e32 v206, v133
	v_mov_b32_e32 v207, v135
	v_mov_b32_e32 v210, v175
	v_mov_b32_e32 v211, v177
	v_pk_mul_f32 v[208:209], v[206:207], v[184:185]
	v_pk_mul_f32 v[212:213], v[210:211], v[182:183]
	v_mov_b32_e32 v175, v176
	v_mov_b32_e32 v133, v134
	v_pk_fma_f32 v[176:177], v[174:175], v[128:129], v[212:213] neg_lo:[0,0,1] neg_hi:[0,0,1]
	v_pk_fma_f32 v[134:135], v[132:133], v[180:181], v[208:209] neg_lo:[0,0,1] neg_hi:[0,0,1]
	v_pk_mul_f32 v[132:133], v[132:133], v[184:185]
	v_pk_mul_f32 v[174:175], v[174:175], v[182:183]
	v_pk_fma_f32 v[132:133], v[206:207], v[180:181], v[132:133]
	v_pk_fma_f32 v[128:129], v[210:211], v[128:129], v[174:175]
	v_cvt_pk_bf16_f32 v132, v132, v133
	v_cvt_pk_bf16_f32 v133, v128, v129
	v_cvt_pk_bf16_f32 v134, v134, v135
	v_cvt_pk_bf16_f32 v135, v176, v177
	global_store_dwordx2 v[178:179], v[132:133], off offset:96
	v_pk_mul_f32 v[128:129], v[78:79], v[78:79]
	v_pk_mul_f32 v[132:133], v[76:77], v[76:77]
	global_store_dwordx2 v[178:179], v[134:135], off offset:64
	v_add_u32_e32 v220, 0x80, v150
	v_bfe_u32 v220, v220, 6, 6
	v_lshl_add_u32 v220, v220, 5, v151
	v_ashrrev_i32_e32 v221, 31, v220
	v_lshl_add_u64 v[220:221], v[220:221], 2, s[58:59]
	global_load_dwordx4 v[222:225], v[220:221], off
	global_load_dwordx4 v[226:229], v[220:221], off offset:16
; __device__ __forceinline__ float dot4(f32x4 v) { return (v[0] * v[0] + v[1] * v[1]) + (v[2] * v[2] + v[3] * v[3]); }
; __device__ __forceinline__ float quad_sum(float s) { s += __shfl_xor(s, 16); s += __shfl_xor(s, 32); return s; }
; __device__ __forceinline__ void st4(bf16_t* p, f32x4 v) { u32x2 w; w.x = cvt_pk_bf16(v[0], v[1]); w.y = cvt_pk_bf16(v[2], v[3]); *(u32x2*)p = w; }
;     __device__ __forceinline__ void operator()(const f32x4 (&acc)[2][2][4][2], const Unit& u, int wr, int wc, int fr, int fq) const {
;     ...
;                 for (int m = 0; m < 4; ++m) { const int row = row0 + ai * HALF + m * 16; float s = 0.f;
; #pragma unroll
;                     for (int bj = 0; bj < 2; ++bj)
; #pragma unroll
;                         for (int n = 0; n < 2; ++n) s += dot4(acc[ai][bj][m][n]);
;                     s = quad_sum(s); const float rstd = 1.0f / sqrtf(s * (1.f / 64.f) + NEPS);
;                     const int srow = row & (SEQL - 1), prow = srow >> 6, pcol = srow & 63;
; #pragma unroll
;                     for (int bj = 0; bj < 2; ++bj) { const int pos = bj ? pcol : prow; f32x4 y1, y2;
;                         rope4(acc[ai][bj][m][0] * rstd * gv[bj][0], acc[ai][bj][m][1] * rstd * gv[bj][1], ropeG + (pos * 16 + 4 * fq) * 2, y1, y2);
;                         bf16_t* dp = isq ? dst + (size_t)row * pitch : KG + ((((size_t)((row >> 12) * 2 + wc) * 64 + (srow >> 6)) * 64 + (srow & 63)) * 64);
;                         st4(dp + 32 * bj + 4 * fq, y1); st4(dp + 32 * bj + 16 + 4 * fq, y2); } }
	v_lshl_add_u32 v220, v205, 5, v151
	v_ashrrev_i32_e32 v221, 31, v220
	v_lshl_add_u64 v[220:221], v[220:221], 2, s[58:59]
	global_load_dwordx4 v[230:233], v[220:221], off
	global_load_dwordx4 v[234:237], v[220:221], off offset:16
	v_pk_mov_b32 v[134:135], v[132:133], v[128:129] op_sel:[1,0]
	v_mov_b32_e32 v133, v129
	v_pk_add_f32 v[128:129], v[134:135], v[132:133]
	v_pk_mul_f32 v[132:133], v[74:75], v[74:75]
	v_pk_mul_f32 v[134:135], v[72:73], v[72:73]
	v_pk_add_f32 v[128:129], v[128:129], v[128:129] op_sel:[0,1] op_sel_hi:[1,0]
	v_pk_mov_b32 v[174:175], v[134:135], v[132:133] op_sel:[1,0]
	v_mov_b32_e32 v135, v133
	v_pk_add_f32 v[132:133], v[174:175], v[134:135]
	v_mul_f32_e32 v134, v64, v64
	v_mul_f32_e32 v135, v65, v65
	v_pk_add_f32 v[132:133], v[132:133], v[132:133] op_sel:[0,1] op_sel_hi:[1,0]
	v_mov_b32_e32 v129, v134
	v_mov_b32_e32 v133, v135
	v_pk_add_f32 v[128:129], v[128:129], v[132:133]
	v_mul_f32_e32 v132, v69, v69
	v_mul_f32_e32 v134, v71, v71
	v_mul_f32_e32 v174, v67, v67
	v_pk_fma_f32 v[132:133], v[68:69], v[68:69], v[132:133] op_sel_hi:[1,1,0]
	v_pk_fma_f32 v[134:135], v[70:71], v[70:71], v[134:135] op_sel_hi:[1,1,0]
	v_mov_b32_e32 v133, v140
	v_mov_b32_e32 v135, v174
	v_pk_add_f32 v[132:133], v[132:133], v[134:135]
	s_nop 0
	v_pk_add_f32 v[128:129], v[128:129], v[132:133]
	s_nop 0
	v_add_f32_e32 v128, v128, v129
	ds_bpermute_b32 v132, v201, v128
	v_add_u32_e32 v129, 48, v150
	s_waitcnt lgkmcnt(0)
	v_add_f32_e32 v128, v128, v132
	ds_bpermute_b32 v132, v202, v128
	s_waitcnt lgkmcnt(0)
	v_add_f32_e32 v128, v128, v132
	v_fmamk_f32 v128, v128, 0x3c800000, v196
	v_cmp_gt_f32_e32 vcc, s49, v128
	v_mul_f32_e32 v132, 0x4f800000, v128
	s_nop 0
	v_cndmask_b32_e32 v128, v128, v132, vcc
	v_sqrt_f32_e32 v132, v128
	s_nop 0
	v_add_u32_e32 v133, -1, v132
	v_fma_f32 v134, -v133, v132, v128
	v_cmp_ge_f32_e64 s[0:1], 0, v134
	v_add_u32_e32 v134, 1, v132
	s_nop 0
	v_cndmask_b32_e64 v133, v132, v133, s[0:1]
	v_fma_f32 v132, -v134, v132, v128
	v_cmp_lt_f32_e64 s[0:1], 0, v132
	s_nop 1
	v_cndmask_b32_e64 v132, v133, v134, s[0:1]
	v_mul_f32_e32 v133, 0x37800000, v132
	v_cndmask_b32_e32 v132, v132, v133, vcc
	v_cmp_class_f32_e32 vcc, v128, v197
	s_nop 1
	v_cndmask_b32_e32 v128, v132, v128, vcc
	v_div_scale_f32 v132, s[0:1], v128, v128, 1.0
	v_rcp_f32_e32 v133, v132
	s_nop 0
	v_fma_f32 v134, -v132, v133, 1.0
	v_fmac_f32_e32 v133, v134, v133
	v_div_scale_f32 v134, vcc, 1.0, v128, 1.0
	v_mul_f32_e32 v135, v134, v133
	v_fma_f32 v140, -v132, v135, v134
	v_fmac_f32_e32 v135, v140, v133
	v_fma_f32 v132, -v132, v135, v134
	v_div_fmas_f32 v132, v132, v133, v135
	v_div_fixup_f32 v128, v132, v128, 1.0
	v_ashrrev_i32_e32 v132, 11, v129
	v_and_b32_e32 v132, -2, v132
	v_add_u32_e32 v132, s69, v132
	v_bfe_u32 v140, v129, 6, 6
	v_ashrrev_i32_e32 v133, 31, v132
	v_lshlrev_b64 v[132:133], 12, v[132:133]
	v_lshlrev_b32_e32 v134, 6, v140
	v_or3_b32 v132, v132, v134, v200
	v_lshlrev_b64 v[178:179], 7, v[132:133]
	v_mad_i64_i32 v[132:133], s[0:1], s6, v129, 0
	v_lshl_add_u64 v[180:181], v[132:133], 1, s[10:11]
	v_pk_mul_f32 v[132:133], v[78:79], v[128:129] op_sel_hi:[1,0]
	v_pk_mul_f32 v[134:135], v[76:77], v[128:129] op_sel_hi:[1,0]
	v_pk_mul_f32 v[184:185], v[160:161], v[132:133]
	v_pk_mul_f32 v[132:133], v[72:73], v[128:129] op_sel_hi:[1,0]
	v_pk_mul_f32 v[182:183], v[162:163], v[134:135]
	v_pk_mul_f32 v[208:209], v[166:167], v[132:133]
	v_lshl_add_u32 v132, v140, 5, v151
	v_ashrrev_i32_e32 v133, 31, v132
	v_pk_mul_f32 v[134:135], v[74:75], v[128:129] op_sel_hi:[1,0]
	v_lshl_add_u64 v[174:175], v[132:133], 2, s[58:59]
	v_pk_mul_f32 v[206:207], v[164:165], v[134:135]
	s_waitcnt vmcnt(10)
	v_mov_b32_e32 v132, v238
	v_mov_b32_e32 v133, v239
	v_mov_b32_e32 v134, v240
	v_mov_b32_e32 v135, v241
	s_nop 0
	v_mov_b32_e32 v174, v242
	v_mov_b32_e32 v175, v243
	v_mov_b32_e32 v176, v244
	v_mov_b32_e32 v177, v245
	v_mul_f32_e32 v140, v48, v48
	v_mov_b32_e32 v210, v133
	v_mov_b32_e32 v211, v135
	v_pk_mul_f32 v[212:213], v[210:211], v[208:209]
	v_mov_b32_e32 v133, v134
	v_mov_b32_e32 v214, v175
	v_mov_b32_e32 v215, v177
	v_pk_fma_f32 v[134:135], v[132:133], v[182:183], v[212:213] neg_lo:[0,0,1] neg_hi:[0,0,1]
	v_pk_mul_f32 v[132:133], v[132:133], v[208:209]
	v_pk_mul_f32 v[216:217], v[214:215], v[206:207]
	v_mov_b32_e32 v175, v176
	v_pk_fma_f32 v[182:183], v[210:211], v[182:183], v[132:133]
	v_lshl_add_u64 v[132:133], s[42:43], 0, v[178:179]
	v_pk_fma_f32 v[176:177], v[174:175], v[184:185], v[216:217] neg_lo:[0,0,1] neg_hi:[0,0,1]
	v_pk_mul_f32 v[174:175], v[174:175], v[206:207]
	v_cndmask_b32_e64 v133, v133, v181, s[92:93]
	v_cndmask_b32_e64 v132, v132, v180, s[92:93]
	v_pk_fma_f32 v[174:175], v[214:215], v[184:185], v[174:175]
	v_lshl_add_u64 v[132:133], v[132:133], 0, v[168:169]
	v_cvt_pk_bf16_f32 v134, v134, v135
	v_cvt_pk_bf16_f32 v135, v176, v177
	global_store_dwordx2 v[132:133], v[134:135], off
	v_cvt_pk_bf16_f32 v134, v182, v183
	v_cvt_pk_bf16_f32 v135, v174, v175
	global_store_dwordx2 v[132:133], v[134:135], off offset:32
	v_pk_mul_f32 v[174:175], v[70:71], v[128:129] op_sel_hi:[1,0]
	v_pk_mul_f32 v[134:135], v[68:69], v[128:129] op_sel_hi:[1,0]
	v_pk_mul_f32 v[178:179], v[64:65], v[128:129] op_sel_hi:[1,0]
	v_pk_mul_f32 v[128:129], v[66:67], v[128:129] op_sel_hi:[1,0]
	v_pk_mul_f32 v[178:179], v[156:157], v[178:179]
	v_pk_mul_f32 v[176:177], v[154:155], v[128:129]
	v_lshl_add_u32 v128, v200, 5, v151
	v_ashrrev_i32_e32 v129, 31, v128
	v_lshl_add_u64 v[128:129], v[128:129], 2, s[58:59]
	s_waitcnt vmcnt(10)
; __device__ __forceinline__ float dot4(f32x4 v) { return (v[0] * v[0] + v[1] * v[1]) + (v[2] * v[2] + v[3] * v[3]); }
; __device__ __forceinline__ float quad_sum(float s) { s += __shfl_xor(s, 16); s += __shfl_xor(s, 32); return s; }
; __device__ __forceinline__ void st4(bf16_t* p, f32x4 v) { u32x2 w; w.x = cvt_pk_bf16(v[0], v[1]); w.y = cvt_pk_bf16(v[2], v[3]); *(u32x2*)p = w; }
;     __device__ __forceinline__ void operator()(const f32x4 (&acc)[2][2][4][2], const Unit& u, int wr, int wc, int fr, int fq) const {
;     ...
;                 for (int m = 0; m < 4; ++m) { const int row = row0 + ai * HALF + m * 16; float s = 0.f;
; #pragma unroll
;                     for (int bj = 0; bj < 2; ++bj)
; #pragma unroll
;                         for (int n = 0; n < 2; ++n) s += dot4(acc[ai][bj][m][n]);
;                     s = quad_sum(s); const float rstd = 1.0f / sqrtf(s * (1.f / 64.f) + NEPS);
;                     const int srow = row & (SEQL - 1), prow = srow >> 6, pcol = srow & 63;
; #pragma unroll
;                     for (int bj = 0; bj < 2; ++bj) { const int pos = bj ? pcol : prow; f32x4 y1, y2;
;                         rope4(acc[ai][bj][m][0] * rstd * gv[bj][0], acc[ai][bj][m][1] * rstd * gv[bj][1], ropeG + (pos * 16 + 4 * fq) * 2, y1, y2);
;                         bf16_t* dp = isq ? dst + (size_t)row * pitch : KG + ((((size_t)((row >> 12) * 2 + wc) * 64 + (srow >> 6)) * 64 + (srow & 63)) * 64);
;                         st4(dp + 32 * bj + 4 * fq, y1); st4(dp + 32 * bj + 16 + 4 * fq, y2); } }
	v_mov_b32_e32 v180, v246
	v_mov_b32_e32 v181, v247
	v_mov_b32_e32 v182, v248
	v_mov_b32_e32 v183, v249
	v_mov_b32_e32 v206, v250
	v_mov_b32_e32 v207, v251
	v_mov_b32_e32 v208, v252
	v_mov_b32_e32 v209, v253
	v_pk_mul_f32 v[134:135], v[158:159], v[134:135]
	v_pk_mul_f32 v[174:175], v[152:153], v[174:175]
	v_mov_b32_e32 v184, v181
	v_mov_b32_e32 v185, v183
	v_mov_b32_e32 v212, v207
	v_mov_b32_e32 v213, v209
	v_mov_b32_e32 v207, v208
	v_mov_b32_e32 v181, v182
	v_pk_mul_f32 v[210:211], v[184:185], v[178:179]
	v_pk_mul_f32 v[214:215], v[212:213], v[176:177]
	v_pk_mul_f32 v[178:179], v[180:181], v[178:179]
	v_pk_mul_f32 v[176:177], v[206:207], v[176:177]
	v_pk_fma_f32 v[208:209], v[206:207], v[174:175], v[214:215] neg_lo:[0,0,1] neg_hi:[0,0,1]
	v_pk_fma_f32 v[182:183], v[180:181], v[134:135], v[210:211] neg_lo:[0,0,1] neg_hi:[0,0,1]
	v_pk_fma_f32 v[174:175], v[212:213], v[174:175], v[176:177]
	v_pk_fma_f32 v[134:135], v[184:185], v[134:135], v[178:179]
	v_cvt_pk_bf16_f32 v176, v182, v183
	v_cvt_pk_bf16_f32 v177, v208, v209
	v_cvt_pk_bf16_f32 v134, v134, v135
	v_cvt_pk_bf16_f32 v135, v174, v175
	global_store_dwordx2 v[132:133], v[176:177], off offset:64
	global_store_dwordx2 v[132:133], v[134:135], off offset:96
	v_add_u32_e32 v220, 0x90, v150
	v_bfe_u32 v220, v220, 6, 6
	v_lshl_add_u32 v220, v220, 5, v151
	v_ashrrev_i32_e32 v221, 31, v220
	v_lshl_add_u64 v[220:221], v[220:221], 2, s[58:59]
	global_load_dwordx4 v[238:241], v[220:221], off
	global_load_dwordx4 v[242:245], v[220:221], off offset:16
	v_lshl_add_u32 v220, v204, 5, v151
	v_ashrrev_i32_e32 v221, 31, v220
	v_lshl_add_u64 v[220:221], v[220:221], 2, s[58:59]
	global_load_dwordx4 v[246:249], v[220:221], off
	global_load_dwordx4 v[250:253], v[220:221], off offset:16
	v_pk_mul_f32 v[132:133], v[62:63], v[62:63]
	v_pk_mul_f32 v[134:135], v[60:61], v[60:61]
	v_add_u32_e32 v178, 0x80, v150
	v_pk_mov_b32 v[174:175], v[134:135], v[132:133] op_sel:[1,0]
	v_mov_b32_e32 v135, v133
	v_pk_add_f32 v[132:133], v[174:175], v[134:135]
	v_pk_mul_f32 v[134:135], v[58:59], v[58:59]
	v_pk_mul_f32 v[174:175], v[56:57], v[56:57]
	v_pk_add_f32 v[132:133], v[132:133], v[132:133] op_sel:[0,1] op_sel_hi:[1,0]
	v_pk_mov_b32 v[176:177], v[174:175], v[134:135] op_sel:[1,0]
	v_mov_b32_e32 v175, v135
	v_pk_add_f32 v[134:135], v[176:177], v[174:175]
	v_mul_f32_e32 v174, v49, v49
	v_pk_add_f32 v[134:135], v[134:135], v[134:135] op_sel:[0,1] op_sel_hi:[1,0]
	v_mov_b32_e32 v133, v140
	v_mov_b32_e32 v135, v174
	v_pk_add_f32 v[132:133], v[132:133], v[134:135]
	v_mul_f32_e32 v134, v53, v53
	v_mul_f32_e32 v175, v50, v50
	v_pk_fma_f32 v[134:135], v[52:53], v[52:53], v[134:135] op_sel_hi:[1,1,0]
	v_mul_f32_e32 v140, v55, v55
	v_mul_f32_e32 v176, v51, v51
	v_mov_b32_e32 v135, v175
	v_pk_fma_f32 v[174:175], v[54:55], v[54:55], v[140:141] op_sel_hi:[1,1,0]
	s_nop 0
	v_mov_b32_e32 v175, v176
	v_pk_add_f32 v[134:135], v[134:135], v[174:175]
	s_nop 0
	v_pk_add_f32 v[132:133], v[132:133], v[134:135]
	s_nop 0
	v_add_f32_e32 v132, v132, v133
	ds_bpermute_b32 v133, v201, v132
	s_waitcnt lgkmcnt(0)
	v_add_f32_e32 v132, v132, v133
	ds_bpermute_b32 v133, v202, v132
	s_waitcnt lgkmcnt(0)
	v_add_f32_e32 v132, v132, v133
	v_fmamk_f32 v132, v132, 0x3c800000, v196
	v_cmp_gt_f32_e32 vcc, s49, v132
	v_mul_f32_e32 v133, 0x4f800000, v132
	s_nop 0
	v_cndmask_b32_e32 v132, v132, v133, vcc
	v_sqrt_f32_e32 v133, v132
	s_nop 0
	v_add_u32_e32 v134, -1, v133
	v_fma_f32 v135, -v134, v133, v132
	v_cmp_ge_f32_e64 s[0:1], 0, v135
	v_add_u32_e32 v135, 1, v133
	s_nop 0
	v_cndmask_b32_e64 v134, v133, v134, s[0:1]
	v_fma_f32 v133, -v135, v133, v132
	v_cmp_lt_f32_e64 s[0:1], 0, v133
	s_nop 1
	v_cndmask_b32_e64 v133, v134, v135, s[0:1]
	v_mul_f32_e32 v134, 0x37800000, v133
	v_cndmask_b32_e32 v133, v133, v134, vcc
	v_cmp_class_f32_e32 vcc, v132, v197
	s_nop 1
	v_cndmask_b32_e32 v132, v133, v132, vcc
	v_div_scale_f32 v133, s[0:1], v132, v132, 1.0
	v_rcp_f32_e32 v134, v133
	s_nop 0
	v_fma_f32 v135, -v133, v134, 1.0
	v_fmac_f32_e32 v134, v135, v134
	v_div_scale_f32 v135, vcc, 1.0, v132, 1.0
	v_mul_f32_e32 v140, v135, v134
	v_fma_f32 v174, -v133, v140, v135
	v_fmac_f32_e32 v140, v174, v134
	v_fma_f32 v133, -v133, v140, v135
	v_div_fmas_f32 v133, v133, v134, v140
	v_ashrrev_i32_e32 v134, 11, v178
	v_and_b32_e32 v134, -2, v134
	v_div_fixup_f32 v132, v133, v132, 1.0
	v_bfe_u32 v133, v178, 6, 6
	v_add_u32_e32 v134, s69, v134
	v_ashrrev_i32_e32 v135, 31, v134
	v_pk_mul_f32 v[176:177], v[62:63], v[132:133] op_sel_hi:[1,0]
	v_lshlrev_b64 v[134:135], 12, v[134:135]
	v_lshlrev_b32_e32 v140, 6, v133
	v_pk_mul_f32 v[210:211], v[160:161], v[176:177]
	v_pk_mul_f32 v[176:177], v[56:57], v[132:133] op_sel_hi:[1,0]
	v_or3_b32 v134, v134, v140, v205
	v_pk_mul_f32 v[214:215], v[166:167], v[176:177]
	v_lshl_add_u32 v176, v133, 5, v151
	v_lshlrev_b64 v[174:175], 7, v[134:135]
	v_mad_i64_i32 v[134:135], s[0:1], s6, v178, 0
	v_pk_mul_f32 v[178:179], v[60:61], v[132:133] op_sel_hi:[1,0]
	v_ashrrev_i32_e32 v177, 31, v176
	v_pk_mul_f32 v[184:185], v[162:163], v[178:179]
	v_pk_mul_f32 v[178:179], v[58:59], v[132:133] op_sel_hi:[1,0]
	v_lshl_add_u64 v[180:181], v[176:177], 2, s[58:59]
	v_pk_mul_f32 v[212:213], v[164:165], v[178:179]
	s_waitcnt vmcnt(10)
; __device__ __forceinline__ float dot4(f32x4 v) { return (v[0] * v[0] + v[1] * v[1]) + (v[2] * v[2] + v[3] * v[3]); }
; __device__ __forceinline__ float quad_sum(float s) { s += __shfl_xor(s, 16); s += __shfl_xor(s, 32); return s; }
; __device__ __forceinline__ void st4(bf16_t* p, f32x4 v) { u32x2 w; w.x = cvt_pk_bf16(v[0], v[1]); w.y = cvt_pk_bf16(v[2], v[3]); *(u32x2*)p = w; }
;     __device__ __forceinline__ void operator()(const f32x4 (&acc)[2][2][4][2], const Unit& u, int wr, int wc, int fr, int fq) const {
;     ...
;                 for (int m = 0; m < 4; ++m) { const int row = row0 + ai * HALF + m * 16; float s = 0.f;
; #pragma unroll
;                     for (int bj = 0; bj < 2; ++bj)
; #pragma unroll
;                         for (int n = 0; n < 2; ++n) s += dot4(acc[ai][bj][m][n]);
;                     s = quad_sum(s); const float rstd = 1.0f / sqrtf(s * (1.f / 64.f) + NEPS);
;                     const int srow = row & (SEQL - 1), prow = srow >> 6, pcol = srow & 63;
; #pragma unroll
;                     for (int bj = 0; bj < 2; ++bj) { const int pos = bj ? pcol : prow; f32x4 y1, y2;
;                         rope4(acc[ai][bj][m][0] * rstd * gv[bj][0], acc[ai][bj][m][1] * rstd * gv[bj][1], ropeG + (pos * 16 + 4 * fq) * 2, y1, y2);
;                         bf16_t* dp = isq ? dst + (size_t)row * pitch : KG + ((((size_t)((row >> 12) * 2 + wc) * 64 + (srow >> 6)) * 64 + (srow & 63)) * 64);
;                         st4(dp + 32 * bj + 4 * fq, y1); st4(dp + 32 * bj + 16 + 4 * fq, y2); } }
	v_mov_b32_e32 v176, v222
	v_mov_b32_e32 v177, v223
	v_mov_b32_e32 v178, v224
	v_mov_b32_e32 v179, v225
	v_mov_b32_e32 v206, v226
	v_mov_b32_e32 v207, v227
	v_mov_b32_e32 v208, v228
	v_mov_b32_e32 v209, v229
	v_lshl_add_u64 v[134:135], v[134:135], 1, s[10:11]
	v_lshl_add_u64 v[174:175], s[42:43], 0, v[174:175]
	v_cndmask_b32_e64 v135, v175, v135, s[92:93]
	v_cndmask_b32_e64 v134, v174, v134, s[92:93]
	v_pk_mul_f32 v[174:175], v[52:53], v[132:133] op_sel_hi:[1,0]
	v_mul_f32_e32 v140, v32, v32
	v_mov_b32_e32 v216, v177
	v_mov_b32_e32 v217, v179
	v_mov_b32_e32 v218, v207
	v_mov_b32_e32 v219, v209
	v_pk_mul_f32 v[182:183], v[216:217], v[214:215]
	v_pk_mul_f32 v[180:181], v[218:219], v[212:213]
	v_mov_b32_e32 v207, v208
	v_mov_b32_e32 v177, v178
	v_pk_fma_f32 v[180:181], v[206:207], v[210:211], v[180:181] neg_lo:[0,0,1] neg_hi:[0,0,1]
	v_pk_fma_f32 v[182:183], v[176:177], v[184:185], v[182:183] neg_lo:[0,0,1] neg_hi:[0,0,1]
	v_pk_mul_f32 v[178:179], v[176:177], v[214:215]
	v_pk_mul_f32 v[176:177], v[206:207], v[212:213]
	v_pk_fma_f32 v[178:179], v[216:217], v[184:185], v[178:179]
	v_pk_fma_f32 v[176:177], v[218:219], v[210:211], v[176:177]
	v_lshl_add_u64 v[184:185], v[134:135], 0, v[168:169]
	v_cvt_pk_bf16_f32 v134, v182, v183
	v_cvt_pk_bf16_f32 v135, v180, v181
	global_store_dwordx2 v[184:185], v[134:135], off
	v_cvt_pk_bf16_f32 v134, v178, v179
	v_cvt_pk_bf16_f32 v135, v176, v177
	global_store_dwordx2 v[184:185], v[134:135], off offset:32
	v_pk_mul_f32 v[134:135], v[54:55], v[132:133] op_sel_hi:[1,0]
	v_pk_mul_f32 v[176:177], v[158:159], v[174:175]
	v_pk_mul_f32 v[178:179], v[152:153], v[134:135]
	v_pk_mul_f32 v[134:135], v[48:49], v[132:133] op_sel_hi:[1,0]
	v_pk_mul_f32 v[132:133], v[50:51], v[132:133] op_sel_hi:[1,0]
	v_pk_mul_f32 v[182:183], v[156:157], v[134:135]
	v_pk_mul_f32 v[180:181], v[154:155], v[132:133]
	s_waitcnt vmcnt(10)
	v_mov_b32_e32 v132, v230
	v_mov_b32_e32 v133, v231
	v_mov_b32_e32 v134, v232
	v_mov_b32_e32 v135, v233
	s_nop 0
	v_mov_b32_e32 v172, v234
	v_mov_b32_e32 v173, v235
	v_mov_b32_e32 v174, v236
	v_mov_b32_e32 v175, v237
	v_mov_b32_e32 v206, v133
	v_mov_b32_e32 v207, v135
	v_mov_b32_e32 v210, v173
	v_mov_b32_e32 v211, v175
	v_pk_mul_f32 v[208:209], v[206:207], v[182:183]
	v_pk_mul_f32 v[212:213], v[210:211], v[180:181]
	v_mov_b32_e32 v173, v174
	v_mov_b32_e32 v133, v134
	v_pk_fma_f32 v[174:175], v[172:173], v[178:179], v[212:213] neg_lo:[0,0,1] neg_hi:[0,0,1]
	v_pk_fma_f32 v[134:135], v[132:133], v[176:177], v[208:209] neg_lo:[0,0,1] neg_hi:[0,0,1]
	v_pk_mul_f32 v[132:133], v[132:133], v[182:183]
	v_pk_mul_f32 v[172:173], v[172:173], v[180:181]
	v_pk_fma_f32 v[132:133], v[206:207], v[176:177], v[132:133]
	v_pk_fma_f32 v[172:173], v[210:211], v[178:179], v[172:173]
	v_cvt_pk_bf16_f32 v134, v134, v135
	v_cvt_pk_bf16_f32 v135, v174, v175
	v_cvt_pk_bf16_f32 v132, v132, v133
	v_cvt_pk_bf16_f32 v133, v172, v173
	global_store_dwordx2 v[184:185], v[134:135], off offset:64
	global_store_dwordx2 v[184:185], v[132:133], off offset:96
	v_add_u32_e32 v220, 0xa0, v150
	v_bfe_u32 v220, v220, 6, 6
	v_lshl_add_u32 v220, v220, 5, v151
	v_ashrrev_i32_e32 v221, 31, v220
	v_lshl_add_u64 v[220:221], v[220:221], 2, s[58:59]
	global_load_dwordx4 v[222:225], v[220:221], off
	global_load_dwordx4 v[226:229], v[220:221], off offset:16
	v_lshl_add_u32 v220, v203, 5, v151
	v_ashrrev_i32_e32 v221, 31, v220
	v_lshl_add_u64 v[220:221], v[220:221], 2, s[58:59]
	global_load_dwordx4 v[230:233], v[220:221], off
	global_load_dwordx4 v[234:237], v[220:221], off offset:16
	v_pk_mul_f32 v[132:133], v[46:47], v[46:47]
	v_pk_mul_f32 v[134:135], v[44:45], v[44:45]
	s_nop 0
	v_pk_mov_b32 v[172:173], v[134:135], v[132:133] op_sel:[1,0]
	v_mov_b32_e32 v135, v133
	v_pk_add_f32 v[132:133], v[172:173], v[134:135]
	v_pk_mul_f32 v[134:135], v[42:43], v[42:43]
	v_pk_mul_f32 v[172:173], v[40:41], v[40:41]
	v_pk_add_f32 v[132:133], v[132:133], v[132:133] op_sel:[0,1] op_sel_hi:[1,0]
	v_pk_mov_b32 v[174:175], v[172:173], v[134:135] op_sel:[1,0]
	v_mov_b32_e32 v173, v135
	v_pk_add_f32 v[134:135], v[174:175], v[172:173]
	v_mul_f32_e32 v172, v33, v33
	v_pk_add_f32 v[134:135], v[134:135], v[134:135] op_sel:[0,1] op_sel_hi:[1,0]
	v_mov_b32_e32 v133, v140
	v_mov_b32_e32 v135, v172
	v_pk_add_f32 v[132:133], v[132:133], v[134:135]
	v_mul_f32_e32 v134, v37, v37
	v_mul_f32_e32 v173, v34, v34
	v_pk_fma_f32 v[134:135], v[36:37], v[36:37], v[134:135] op_sel_hi:[1,1,0]
	v_mul_f32_e32 v140, v39, v39
	v_mul_f32_e32 v174, v35, v35
	v_mov_b32_e32 v135, v173
	v_pk_fma_f32 v[172:173], v[38:39], v[38:39], v[140:141] op_sel_hi:[1,1,0]
	s_nop 0
	v_mov_b32_e32 v173, v174
	v_pk_add_f32 v[134:135], v[134:135], v[172:173]
	s_nop 0
	v_pk_add_f32 v[132:133], v[132:133], v[134:135]
	s_nop 0
	v_add_f32_e32 v132, v132, v133
	ds_bpermute_b32 v134, v201, v132
	v_add_u32_e32 v133, 0x90, v150
	s_waitcnt lgkmcnt(0)
	v_add_f32_e32 v132, v132, v134
	ds_bpermute_b32 v134, v202, v132
	s_waitcnt lgkmcnt(0)
; __device__ __forceinline__ float dot4(f32x4 v) { return (v[0] * v[0] + v[1] * v[1]) + (v[2] * v[2] + v[3] * v[3]); }
; __device__ __forceinline__ float quad_sum(float s) { s += __shfl_xor(s, 16); s += __shfl_xor(s, 32); return s; }
; __device__ __forceinline__ void st4(bf16_t* p, f32x4 v) { u32x2 w; w.x = cvt_pk_bf16(v[0], v[1]); w.y = cvt_pk_bf16(v[2], v[3]); *(u32x2*)p = w; }
;     __device__ __forceinline__ void operator()(const f32x4 (&acc)[2][2][4][2], const Unit& u, int wr, int wc, int fr, int fq) const {
;     ...
;                 for (int m = 0; m < 4; ++m) { const int row = row0 + ai * HALF + m * 16; float s = 0.f;
; #pragma unroll
;                     for (int bj = 0; bj < 2; ++bj)
; #pragma unroll
;                         for (int n = 0; n < 2; ++n) s += dot4(acc[ai][bj][m][n]);
;                     s = quad_sum(s); const float rstd = 1.0f / sqrtf(s * (1.f / 64.f) + NEPS);
;                     const int srow = row & (SEQL - 1), prow = srow >> 6, pcol = srow & 63;
; #pragma unroll
;                     for (int bj = 0; bj < 2; ++bj) { const int pos = bj ? pcol : prow; f32x4 y1, y2;
;                         rope4(acc[ai][bj][m][0] * rstd * gv[bj][0], acc[ai][bj][m][1] * rstd * gv[bj][1], ropeG + (pos * 16 + 4 * fq) * 2, y1, y2);
;                         bf16_t* dp = isq ? dst + (size_t)row * pitch : KG + ((((size_t)((row >> 12) * 2 + wc) * 64 + (srow >> 6)) * 64 + (srow & 63)) * 64);
;                         st4(dp + 32 * bj + 4 * fq, y1); st4(dp + 32 * bj + 16 + 4 * fq, y2); } }
	v_add_f32_e32 v132, v132, v134
	v_fmamk_f32 v132, v132, 0x3c800000, v196
	v_cmp_gt_f32_e32 vcc, s49, v132
	v_mul_f32_e32 v134, 0x4f800000, v132
	s_nop 0
	v_cndmask_b32_e32 v132, v132, v134, vcc
	v_sqrt_f32_e32 v134, v132
	s_nop 0
	v_add_u32_e32 v135, -1, v134
	v_fma_f32 v140, -v135, v134, v132
	v_cmp_ge_f32_e64 s[0:1], 0, v140
	v_add_u32_e32 v140, 1, v134
	s_nop 0
	v_cndmask_b32_e64 v135, v134, v135, s[0:1]
	v_fma_f32 v134, -v140, v134, v132
	v_cmp_lt_f32_e64 s[0:1], 0, v134
	s_nop 1
	v_cndmask_b32_e64 v134, v135, v140, s[0:1]
	v_mul_f32_e32 v135, 0x37800000, v134
	v_cndmask_b32_e32 v134, v134, v135, vcc
	v_cmp_class_f32_e32 vcc, v132, v197
	s_nop 1
	v_cndmask_b32_e32 v132, v134, v132, vcc
	v_div_scale_f32 v134, s[0:1], v132, v132, 1.0
	v_rcp_f32_e32 v135, v134
	s_nop 0
	v_fma_f32 v140, -v134, v135, 1.0
	v_fmac_f32_e32 v135, v140, v135
	v_div_scale_f32 v140, vcc, 1.0, v132, 1.0
	v_mul_f32_e32 v172, v140, v135
	v_fma_f32 v173, -v134, v172, v140
	v_fmac_f32_e32 v172, v173, v135
	v_fma_f32 v134, -v134, v172, v140
	v_div_fmas_f32 v134, v134, v135, v172
	v_div_fixup_f32 v132, v134, v132, 1.0
	v_ashrrev_i32_e32 v134, 11, v133
	v_and_b32_e32 v134, -2, v134
	v_pk_mul_f32 v[174:175], v[46:47], v[132:133] op_sel_hi:[1,0]
	v_bfe_u32 v140, v133, 6, 6
	v_add_u32_e32 v134, s69, v134
	v_pk_mul_f32 v[206:207], v[160:161], v[174:175]
	v_pk_mul_f32 v[174:175], v[40:41], v[132:133] op_sel_hi:[1,0]
	v_ashrrev_i32_e32 v135, 31, v134
	v_pk_mul_f32 v[210:211], v[166:167], v[174:175]
	v_lshl_add_u32 v174, v140, 5, v151
	v_lshlrev_b64 v[134:135], 12, v[134:135]
	v_lshlrev_b32_e32 v172, 6, v140
	v_pk_mul_f32 v[176:177], v[44:45], v[132:133] op_sel_hi:[1,0]
	v_ashrrev_i32_e32 v175, 31, v174
	v_or3_b32 v134, v134, v172, v204
	v_pk_mul_f32 v[204:205], v[162:163], v[176:177]
	v_pk_mul_f32 v[176:177], v[42:43], v[132:133] op_sel_hi:[1,0]
	v_lshl_add_u64 v[178:179], v[174:175], 2, s[58:59]
	v_pk_mul_f32 v[208:209], v[164:165], v[176:177]
	s_waitcnt vmcnt(10)
	v_mov_b32_e32 v174, v238
	v_mov_b32_e32 v175, v239
	v_mov_b32_e32 v176, v240
	v_mov_b32_e32 v177, v241
	v_mov_b32_e32 v182, v242
	v_mov_b32_e32 v183, v243
	v_mov_b32_e32 v184, v244
	v_mov_b32_e32 v185, v245
	v_lshlrev_b64 v[172:173], 7, v[134:135]
	v_mad_i64_i32 v[134:135], s[0:1], s6, v133, 0
	v_lshl_add_u64 v[134:135], v[134:135], 1, s[10:11]
	v_lshl_add_u64 v[172:173], s[42:43], 0, v[172:173]
	v_cndmask_b32_e64 v135, v173, v135, s[92:93]
	v_cndmask_b32_e64 v134, v172, v134, s[92:93]
	v_pk_mul_f32 v[172:173], v[36:37], v[132:133] op_sel_hi:[1,0]
	v_mul_f32_e32 v140, v16, v16
	v_mov_b32_e32 v212, v175
	v_mov_b32_e32 v213, v177
	v_mov_b32_e32 v214, v183
	v_mov_b32_e32 v215, v185
	v_pk_mul_f32 v[180:181], v[212:213], v[210:211]
	v_pk_mul_f32 v[178:179], v[214:215], v[208:209]
	v_mov_b32_e32 v183, v184
	v_mov_b32_e32 v175, v176
	v_pk_fma_f32 v[178:179], v[182:183], v[206:207], v[178:179] neg_lo:[0,0,1] neg_hi:[0,0,1]
	v_pk_fma_f32 v[180:181], v[174:175], v[204:205], v[180:181] neg_lo:[0,0,1] neg_hi:[0,0,1]
	v_pk_mul_f32 v[176:177], v[174:175], v[210:211]
	v_pk_mul_f32 v[174:175], v[182:183], v[208:209]
	v_pk_fma_f32 v[176:177], v[212:213], v[204:205], v[176:177]
	v_pk_fma_f32 v[174:175], v[214:215], v[206:207], v[174:175]
	v_lshl_add_u64 v[182:183], v[134:135], 0, v[168:169]
	v_cvt_pk_bf16_f32 v134, v180, v181
	v_cvt_pk_bf16_f32 v135, v178, v179
	global_store_dwordx2 v[182:183], v[134:135], off
	v_cvt_pk_bf16_f32 v134, v176, v177
	v_cvt_pk_bf16_f32 v135, v174, v175
	global_store_dwordx2 v[182:183], v[134:135], off offset:32
	v_pk_mul_f32 v[134:135], v[38:39], v[132:133] op_sel_hi:[1,0]
	v_pk_mul_f32 v[174:175], v[158:159], v[172:173]
	v_pk_mul_f32 v[176:177], v[152:153], v[134:135]
	v_pk_mul_f32 v[134:135], v[32:33], v[132:133] op_sel_hi:[1,0]
	v_pk_mul_f32 v[132:133], v[34:35], v[132:133] op_sel_hi:[1,0]
	v_pk_mul_f32 v[180:181], v[156:157], v[134:135]
	v_pk_mul_f32 v[178:179], v[154:155], v[132:133]
	s_waitcnt vmcnt(10)
	v_mov_b32_e32 v132, v246
	v_mov_b32_e32 v133, v247
	v_mov_b32_e32 v134, v248
	v_mov_b32_e32 v135, v249
	s_nop 0
	v_mov_b32_e32 v170, v250
	v_mov_b32_e32 v171, v251
	v_mov_b32_e32 v172, v252
	v_mov_b32_e32 v173, v253
	v_mov_b32_e32 v184, v133
	v_mov_b32_e32 v185, v135
	v_mov_b32_e32 v206, v171
	v_mov_b32_e32 v207, v173
	v_pk_mul_f32 v[204:205], v[184:185], v[180:181]
	v_pk_mul_f32 v[208:209], v[206:207], v[178:179]
	v_mov_b32_e32 v171, v172
	v_mov_b32_e32 v133, v134
	v_pk_fma_f32 v[172:173], v[170:171], v[176:177], v[208:209] neg_lo:[0,0,1] neg_hi:[0,0,1]
	v_pk_fma_f32 v[134:135], v[132:133], v[174:175], v[204:205] neg_lo:[0,0,1] neg_hi:[0,0,1]
	v_pk_mul_f32 v[132:133], v[132:133], v[180:181]
	v_pk_mul_f32 v[170:171], v[170:171], v[178:179]
	v_pk_fma_f32 v[132:133], v[184:185], v[174:175], v[132:133]
	v_pk_fma_f32 v[170:171], v[206:207], v[176:177], v[170:171]
	v_cvt_pk_bf16_f32 v134, v134, v135
	v_cvt_pk_bf16_f32 v135, v172, v173
	v_cvt_pk_bf16_f32 v132, v132, v133
	v_cvt_pk_bf16_f32 v133, v170, v171
	global_store_dwordx2 v[182:183], v[134:135], off offset:64
	global_store_dwordx2 v[182:183], v[132:133], off offset:96
	v_add_u32_e32 v220, 0xb0, v150
	v_bfe_u32 v220, v220, 6, 6
	v_lshl_add_u32 v220, v220, 5, v151
	v_ashrrev_i32_e32 v221, 31, v220
	v_lshl_add_u64 v[220:221], v[220:221], 2, s[58:59]
	global_load_dwordx4 v[238:241], v[220:221], off
	global_load_dwordx4 v[242:245], v[220:221], off offset:16
	v_lshl_add_u32 v220, v200, 5, v151
	v_ashrrev_i32_e32 v221, 31, v220
	v_lshl_add_u64 v[220:221], v[220:221], 2, s[58:59]
	global_load_dwordx4 v[246:249], v[220:221], off
	global_load_dwordx4 v[250:253], v[220:221], off offset:16
	v_pk_mul_f32 v[132:133], v[30:31], v[30:31]
	v_pk_mul_f32 v[134:135], v[28:29], v[28:29]
	s_nop 0
	v_pk_mov_b32 v[170:171], v[134:135], v[132:133] op_sel:[1,0]
	v_mov_b32_e32 v135, v133
	v_pk_add_f32 v[132:133], v[170:171], v[134:135]
	v_pk_mul_f32 v[134:135], v[26:27], v[26:27]
	v_pk_mul_f32 v[170:171], v[24:25], v[24:25]
	v_pk_add_f32 v[132:133], v[132:133], v[132:133] op_sel:[0,1] op_sel_hi:[1,0]
	v_pk_mov_b32 v[172:173], v[170:171], v[134:135] op_sel:[1,0]
	v_mov_b32_e32 v171, v135
	v_pk_add_f32 v[134:135], v[172:173], v[170:171]
	v_mul_f32_e32 v170, v17, v17
	v_pk_add_f32 v[134:135], v[134:135], v[134:135] op_sel:[0,1] op_sel_hi:[1,0]
	v_mov_b32_e32 v133, v140
	v_mov_b32_e32 v135, v170
	v_pk_add_f32 v[132:133], v[132:133], v[134:135]
	v_mul_f32_e32 v134, v21, v21
	v_mul_f32_e32 v171, v18, v18
	v_pk_fma_f32 v[134:135], v[20:21], v[20:21], v[134:135] op_sel_hi:[1,1,0]
	v_mul_f32_e32 v140, v23, v23
	v_mul_f32_e32 v172, v19, v19
	v_mov_b32_e32 v135, v171
	v_pk_fma_f32 v[170:171], v[22:23], v[22:23], v[140:141] op_sel_hi:[1,1,0]
	s_nop 0
	v_mov_b32_e32 v171, v172
	v_pk_add_f32 v[134:135], v[134:135], v[170:171]
	s_nop 0
	v_pk_add_f32 v[132:133], v[132:133], v[134:135]
	s_nop 0
	v_add_f32_e32 v132, v132, v133
	ds_bpermute_b32 v134, v201, v132
	v_add_u32_e32 v133, 0xa0, v150
	s_waitcnt lgkmcnt(0)
; __device__ __forceinline__ float dot4(f32x4 v) { return (v[0] * v[0] + v[1] * v[1]) + (v[2] * v[2] + v[3] * v[3]); }
; __device__ __forceinline__ float quad_sum(float s) { s += __shfl_xor(s, 16); s += __shfl_xor(s, 32); return s; }
; __device__ __forceinline__ void st4(bf16_t* p, f32x4 v) { u32x2 w; w.x = cvt_pk_bf16(v[0], v[1]); w.y = cvt_pk_bf16(v[2], v[3]); *(u32x2*)p = w; }
;     __device__ __forceinline__ void operator()(const f32x4 (&acc)[2][2][4][2], const Unit& u, int wr, int wc, int fr, int fq) const {
;     ...
;                 for (int m = 0; m < 4; ++m) { const int row = row0 + ai * HALF + m * 16; float s = 0.f;
; #pragma unroll
;                     for (int bj = 0; bj < 2; ++bj)
; #pragma unroll
;                         for (int n = 0; n < 2; ++n) s += dot4(acc[ai][bj][m][n]);
;                     s = quad_sum(s); const float rstd = 1.0f / sqrtf(s * (1.f / 64.f) + NEPS);
;                     const int srow = row & (SEQL - 1), prow = srow >> 6, pcol = srow & 63;
; #pragma unroll
;                     for (int bj = 0; bj < 2; ++bj) { const int pos = bj ? pcol : prow; f32x4 y1, y2;
;                         rope4(acc[ai][bj][m][0] * rstd * gv[bj][0], acc[ai][bj][m][1] * rstd * gv[bj][1], ropeG + (pos * 16 + 4 * fq) * 2, y1, y2);
;                         bf16_t* dp = isq ? dst + (size_t)row * pitch : KG + ((((size_t)((row >> 12) * 2 + wc) * 64 + (srow >> 6)) * 64 + (srow & 63)) * 64);
;                         st4(dp + 32 * bj + 4 * fq, y1); st4(dp + 32 * bj + 16 + 4 * fq, y2); } }
	v_add_f32_e32 v132, v132, v134
	ds_bpermute_b32 v134, v202, v132
	s_waitcnt lgkmcnt(0)
	v_add_f32_e32 v132, v132, v134
	v_fmamk_f32 v132, v132, 0x3c800000, v196
	v_cmp_gt_f32_e32 vcc, s49, v132
	v_mul_f32_e32 v134, 0x4f800000, v132
	s_nop 0
	v_cndmask_b32_e32 v132, v132, v134, vcc
	v_sqrt_f32_e32 v134, v132
	s_nop 0
	v_add_u32_e32 v135, -1, v134
	v_fma_f32 v140, -v135, v134, v132
	v_cmp_ge_f32_e64 s[0:1], 0, v140
	v_add_u32_e32 v140, 1, v134
	s_nop 0
	v_cndmask_b32_e64 v135, v134, v135, s[0:1]
	v_fma_f32 v134, -v140, v134, v132
	v_cmp_lt_f32_e64 s[0:1], 0, v134
	s_nop 1
	v_cndmask_b32_e64 v134, v135, v140, s[0:1]
	v_mul_f32_e32 v135, 0x37800000, v134
	v_cndmask_b32_e32 v134, v134, v135, vcc
	v_cmp_class_f32_e32 vcc, v132, v197
	s_nop 1
	v_cndmask_b32_e32 v132, v134, v132, vcc
	v_div_scale_f32 v134, s[0:1], v132, v132, 1.0
	v_rcp_f32_e32 v135, v134
	s_nop 0
	v_fma_f32 v140, -v134, v135, 1.0
	v_fmac_f32_e32 v135, v140, v135
	v_div_scale_f32 v140, vcc, 1.0, v132, 1.0
	v_mul_f32_e32 v170, v140, v135
	v_fma_f32 v171, -v134, v170, v140
	v_fmac_f32_e32 v170, v171, v135
	v_fma_f32 v134, -v134, v170, v140
	v_div_fmas_f32 v134, v134, v135, v170
	v_div_fixup_f32 v132, v134, v132, 1.0
	v_pk_mul_f32 v[172:173], v[30:31], v[132:133] op_sel_hi:[1,0]
	v_bfe_u32 v140, v133, 6, 6
	v_pk_mul_f32 v[204:205], v[160:161], v[172:173]
	v_pk_mul_f32 v[172:173], v[24:25], v[132:133] op_sel_hi:[1,0]
	v_pk_mul_f32 v[174:175], v[28:29], v[132:133] op_sel_hi:[1,0]
	v_pk_mul_f32 v[208:209], v[166:167], v[172:173]
	v_lshl_add_u32 v172, v140, 5, v151
	v_ashrrev_i32_e32 v173, 31, v172
	v_pk_mul_f32 v[184:185], v[162:163], v[174:175]
	v_pk_mul_f32 v[174:175], v[26:27], v[132:133] op_sel_hi:[1,0]
	v_lshl_add_u64 v[176:177], v[172:173], 2, s[58:59]
	v_pk_mul_f32 v[206:207], v[164:165], v[174:175]
	s_waitcnt vmcnt(10)
	v_mov_b32_e32 v172, v222
	v_mov_b32_e32 v173, v223
	v_mov_b32_e32 v174, v224
	v_mov_b32_e32 v175, v225
	v_mov_b32_e32 v180, v226
	v_mov_b32_e32 v181, v227
	v_mov_b32_e32 v182, v228
	v_mov_b32_e32 v183, v229
	v_ashrrev_i32_e32 v134, 11, v133
	v_and_b32_e32 v134, -2, v134
	v_add_u32_e32 v134, s69, v134
	v_ashrrev_i32_e32 v135, 31, v134
	v_lshlrev_b64 v[134:135], 12, v[134:135]
	v_lshlrev_b32_e32 v170, 6, v140
	v_or3_b32 v134, v134, v170, v203
	v_lshlrev_b64 v[170:171], 7, v[134:135]
	v_mad_i64_i32 v[134:135], s[0:1], s6, v133, 0
	v_lshl_add_u64 v[134:135], v[134:135], 1, s[10:11]
	v_lshl_add_u64 v[170:171], s[42:43], 0, v[170:171]
	v_cndmask_b32_e64 v135, v171, v135, s[92:93]
	v_cndmask_b32_e64 v134, v170, v134, s[92:93]
	v_pk_mul_f32 v[170:171], v[20:21], v[132:133] op_sel_hi:[1,0]
	v_mul_f32_e32 v140, v2, v2
	v_mov_b32_e32 v210, v173
	v_mov_b32_e32 v211, v175
	v_mov_b32_e32 v212, v181
	v_mov_b32_e32 v213, v183
	v_pk_mul_f32 v[178:179], v[210:211], v[208:209]
	v_pk_mul_f32 v[176:177], v[212:213], v[206:207]
	v_mov_b32_e32 v181, v182
	v_mov_b32_e32 v173, v174
	v_pk_fma_f32 v[176:177], v[180:181], v[204:205], v[176:177] neg_lo:[0,0,1] neg_hi:[0,0,1]
	v_pk_fma_f32 v[178:179], v[172:173], v[184:185], v[178:179] neg_lo:[0,0,1] neg_hi:[0,0,1]
	v_pk_mul_f32 v[174:175], v[172:173], v[208:209]
	v_pk_mul_f32 v[172:173], v[180:181], v[206:207]
	v_pk_fma_f32 v[174:175], v[210:211], v[184:185], v[174:175]
	v_pk_fma_f32 v[172:173], v[212:213], v[204:205], v[172:173]
	v_lshl_add_u64 v[180:181], v[134:135], 0, v[168:169]
	v_cvt_pk_bf16_f32 v134, v178, v179
	v_cvt_pk_bf16_f32 v135, v176, v177
	global_store_dwordx2 v[180:181], v[134:135], off
	v_cvt_pk_bf16_f32 v134, v174, v175
	v_cvt_pk_bf16_f32 v135, v172, v173
	global_store_dwordx2 v[180:181], v[134:135], off offset:32
	v_pk_mul_f32 v[134:135], v[22:23], v[132:133] op_sel_hi:[1,0]
	v_pk_mul_f32 v[174:175], v[158:159], v[170:171]
	v_pk_mul_f32 v[176:177], v[152:153], v[134:135]
	v_pk_mul_f32 v[134:135], v[16:17], v[132:133] op_sel_hi:[1,0]
	v_pk_mul_f32 v[132:133], v[18:19], v[132:133] op_sel_hi:[1,0]
	v_pk_mul_f32 v[182:183], v[156:157], v[134:135]
	v_pk_mul_f32 v[178:179], v[154:155], v[132:133]
	s_waitcnt vmcnt(10)
	v_mov_b32_e32 v132, v230
	v_mov_b32_e32 v133, v231
	v_mov_b32_e32 v134, v232
	v_mov_b32_e32 v135, v233
	v_mov_b32_e32 v170, v234
	v_mov_b32_e32 v171, v235
	v_mov_b32_e32 v172, v236
	v_mov_b32_e32 v173, v237
	v_mov_b32_e32 v130, v133
	v_mov_b32_e32 v131, v135
	v_mov_b32_e32 v204, v171
	v_mov_b32_e32 v205, v173
	v_pk_mul_f32 v[184:185], v[130:131], v[182:183]
	v_pk_mul_f32 v[206:207], v[204:205], v[178:179]
	v_mov_b32_e32 v171, v172
	v_mov_b32_e32 v133, v134
	v_pk_fma_f32 v[172:173], v[170:171], v[176:177], v[206:207] neg_lo:[0,0,1] neg_hi:[0,0,1]
	v_pk_fma_f32 v[134:135], v[132:133], v[174:175], v[184:185] neg_lo:[0,0,1] neg_hi:[0,0,1]
	v_pk_mul_f32 v[132:133], v[132:133], v[182:183]
	v_pk_mul_f32 v[170:171], v[170:171], v[178:179]
	v_pk_fma_f32 v[130:131], v[130:131], v[174:175], v[132:133]
	v_pk_fma_f32 v[170:171], v[204:205], v[176:177], v[170:171]
	v_cvt_pk_bf16_f32 v132, v134, v135
	v_cvt_pk_bf16_f32 v133, v172, v173
	v_cvt_pk_bf16_f32 v130, v130, v131
	v_cvt_pk_bf16_f32 v131, v170, v171
	global_store_dwordx2 v[180:181], v[132:133], off offset:64
	global_store_dwordx2 v[180:181], v[130:131], off offset:96
	v_pk_mul_f32 v[130:131], v[14:15], v[14:15]
	v_pk_mul_f32 v[132:133], v[12:13], v[12:13]
	s_nop 0
	v_pk_mov_b32 v[134:135], v[132:133], v[130:131] op_sel:[1,0]
	v_mov_b32_e32 v133, v131
	v_pk_add_f32 v[130:131], v[134:135], v[132:133]
	v_pk_mul_f32 v[132:133], v[10:11], v[10:11]
	v_pk_mul_f32 v[134:135], v[8:9], v[8:9]
	v_pk_add_f32 v[130:131], v[130:131], v[130:131] op_sel:[0,1] op_sel_hi:[1,0]
	v_pk_mov_b32 v[170:171], v[134:135], v[132:133] op_sel:[1,0]
	v_mov_b32_e32 v135, v133
	v_pk_add_f32 v[132:133], v[170:171], v[134:135]
	v_mul_f32_e32 v134, v0, v0
	v_mul_f32_e32 v135, v1, v1
	v_pk_add_f32 v[132:133], v[132:133], v[132:133] op_sel:[0,1] op_sel_hi:[1,0]
	v_mov_b32_e32 v131, v134
	v_mov_b32_e32 v133, v135
	v_pk_add_f32 v[130:131], v[130:131], v[132:133]
	v_mul_f32_e32 v132, v5, v5
	v_mul_f32_e32 v134, v7, v7
	v_mul_f32_e32 v170, v3, v3
	v_pk_fma_f32 v[132:133], v[4:5], v[4:5], v[132:133] op_sel_hi:[1,1,0]
	v_pk_fma_f32 v[134:135], v[6:7], v[6:7], v[134:135] op_sel_hi:[1,1,0]
	v_mov_b32_e32 v133, v140
	v_mov_b32_e32 v135, v170
	v_pk_add_f32 v[132:133], v[132:133], v[134:135]
	s_nop 0
	v_pk_add_f32 v[130:131], v[130:131], v[132:133]
	s_nop 0
	v_add_f32_e32 v130, v130, v131
	ds_bpermute_b32 v132, v201, v130
	v_add_u32_e32 v131, 0xb0, v150
	s_waitcnt lgkmcnt(0)
; __device__ __forceinline__ float dot4(f32x4 v) { return (v[0] * v[0] + v[1] * v[1]) + (v[2] * v[2] + v[3] * v[3]); }
; __device__ __forceinline__ float quad_sum(float s) { s += __shfl_xor(s, 16); s += __shfl_xor(s, 32); return s; }
; __device__ __forceinline__ void st4(bf16_t* p, f32x4 v) { u32x2 w; w.x = cvt_pk_bf16(v[0], v[1]); w.y = cvt_pk_bf16(v[2], v[3]); *(u32x2*)p = w; }
;     __device__ __forceinline__ void operator()(const f32x4 (&acc)[2][2][4][2], const Unit& u, int wr, int wc, int fr, int fq) const {
;     ...
;                 for (int m = 0; m < 4; ++m) { const int row = row0 + ai * HALF + m * 16; float s = 0.f;
; #pragma unroll
;                     for (int bj = 0; bj < 2; ++bj)
; #pragma unroll
;                         for (int n = 0; n < 2; ++n) s += dot4(acc[ai][bj][m][n]);
;                     s = quad_sum(s); const float rstd = 1.0f / sqrtf(s * (1.f / 64.f) + NEPS);
;                     const int srow = row & (SEQL - 1), prow = srow >> 6, pcol = srow & 63;
; #pragma unroll
;                     for (int bj = 0; bj < 2; ++bj) { const int pos = bj ? pcol : prow; f32x4 y1, y2;
;                         rope4(acc[ai][bj][m][0] * rstd * gv[bj][0], acc[ai][bj][m][1] * rstd * gv[bj][1], ropeG + (pos * 16 + 4 * fq) * 2, y1, y2);
;                         bf16_t* dp = isq ? dst + (size_t)row * pitch : KG + ((((size_t)((row >> 12) * 2 + wc) * 64 + (srow >> 6)) * 64 + (srow & 63)) * 64);
;                         st4(dp + 32 * bj + 4 * fq, y1); st4(dp + 32 * bj + 16 + 4 * fq, y2); } }
	v_add_f32_e32 v130, v130, v132
	ds_bpermute_b32 v132, v202, v130
	s_waitcnt lgkmcnt(0)
	v_add_f32_e32 v130, v130, v132
	v_fmamk_f32 v130, v130, 0x3c800000, v196
	v_cmp_gt_f32_e32 vcc, s49, v130
	v_mul_f32_e32 v132, 0x4f800000, v130
	s_nop 0
	v_cndmask_b32_e32 v130, v130, v132, vcc
	v_sqrt_f32_e32 v132, v130
	s_nop 0
	v_add_u32_e32 v133, -1, v132
	v_fma_f32 v134, -v133, v132, v130
	v_cmp_ge_f32_e64 s[0:1], 0, v134
	v_add_u32_e32 v134, 1, v132
	s_nop 0
	v_cndmask_b32_e64 v133, v132, v133, s[0:1]
	v_fma_f32 v132, -v134, v132, v130
	v_cmp_lt_f32_e64 s[0:1], 0, v132
	s_nop 1
	v_cndmask_b32_e64 v132, v133, v134, s[0:1]
	v_mul_f32_e32 v133, 0x37800000, v132
	v_cndmask_b32_e32 v132, v132, v133, vcc
	v_cmp_class_f32_e32 vcc, v130, v197
	s_nop 1
	v_cndmask_b32_e32 v130, v132, v130, vcc
	v_div_scale_f32 v132, s[0:1], v130, v130, 1.0
	v_rcp_f32_e32 v133, v132
	s_nop 0
	v_fma_f32 v134, -v132, v133, 1.0
	v_fmac_f32_e32 v133, v134, v133
	v_div_scale_f32 v134, vcc, 1.0, v130, 1.0
	v_mul_f32_e32 v135, v134, v133
	v_fma_f32 v140, -v132, v135, v134
	v_fmac_f32_e32 v135, v140, v133
	v_fma_f32 v132, -v132, v135, v134
	v_div_fmas_f32 v132, v132, v133, v135
	v_div_fixup_f32 v130, v132, v130, 1.0
	v_pk_mul_f32 v[170:171], v[14:15], v[130:131] op_sel_hi:[1,0]
	v_bfe_u32 v140, v131, 6, 6
	v_pk_mul_f32 v[176:177], v[160:161], v[170:171]
	v_pk_mul_f32 v[160:161], v[8:9], v[130:131] op_sel_hi:[1,0]
	v_pk_mul_f32 v[172:173], v[12:13], v[130:131] op_sel_hi:[1,0]
	v_pk_mul_f32 v[180:181], v[166:167], v[160:161]
	v_lshl_add_u32 v160, v140, 5, v151
	v_pk_mul_f32 v[174:175], v[162:163], v[172:173]
	v_pk_mul_f32 v[162:163], v[10:11], v[130:131] op_sel_hi:[1,0]
	v_ashrrev_i32_e32 v161, 31, v160
	v_pk_mul_f32 v[178:179], v[164:165], v[162:163]
	v_lshl_add_u64 v[164:165], v[160:161], 2, s[58:59]
	s_waitcnt vmcnt(6)
	v_mov_b32_e32 v160, v238
	v_mov_b32_e32 v161, v239
	v_mov_b32_e32 v162, v240
	v_mov_b32_e32 v163, v241
	v_mov_b32_e32 v170, v242
	v_mov_b32_e32 v171, v243
	v_mov_b32_e32 v172, v244
	v_mov_b32_e32 v173, v245
	v_ashrrev_i32_e32 v132, 11, v131
	v_and_b32_e32 v132, -2, v132
	v_add_u32_e32 v132, s69, v132
	v_ashrrev_i32_e32 v133, 31, v132
	v_lshlrev_b64 v[132:133], 12, v[132:133]
	v_lshlrev_b32_e32 v134, 6, v140
	v_or3_b32 v132, v132, v134, v200
	v_lshlrev_b64 v[134:135], 7, v[132:133]
	v_mad_i64_i32 v[132:133], s[0:1], s6, v131, 0
	v_lshl_add_u64 v[132:133], v[132:133], 1, s[10:11]
	v_lshl_add_u64 v[134:135], s[42:43], 0, v[134:135]
	v_cndmask_b32_e64 v133, v135, v133, s[92:93]
	v_cndmask_b32_e64 v132, v134, v132, s[92:93]
	v_lshl_add_u64 v[132:133], v[132:133], 0, v[168:169]
	v_mov_b32_e32 v182, v161
	v_mov_b32_e32 v183, v163
	v_mov_b32_e32 v184, v171
	v_mov_b32_e32 v185, v173
	v_pk_mul_f32 v[166:167], v[182:183], v[180:181]
	v_pk_mul_f32 v[164:165], v[184:185], v[178:179]
	v_mov_b32_e32 v171, v172
	v_mov_b32_e32 v161, v162
	v_pk_fma_f32 v[164:165], v[170:171], v[176:177], v[164:165] neg_lo:[0,0,1] neg_hi:[0,0,1]
	v_pk_fma_f32 v[166:167], v[160:161], v[174:175], v[166:167] neg_lo:[0,0,1] neg_hi:[0,0,1]
	v_pk_mul_f32 v[162:163], v[160:161], v[180:181]
	v_pk_mul_f32 v[160:161], v[170:171], v[178:179]
	v_pk_fma_f32 v[162:163], v[182:183], v[174:175], v[162:163]
	v_pk_fma_f32 v[160:161], v[184:185], v[176:177], v[160:161]
	v_cvt_pk_bf16_f32 v134, v166, v167
	v_cvt_pk_bf16_f32 v135, v164, v165
	global_store_dwordx2 v[132:133], v[134:135], off
	v_cvt_pk_bf16_f32 v134, v162, v163
	v_cvt_pk_bf16_f32 v135, v160, v161
	global_store_dwordx2 v[132:133], v[134:135], off offset:32
	v_pk_mul_f32 v[134:135], v[6:7], v[130:131] op_sel_hi:[1,0]
	v_pk_mul_f32 v[160:161], v[4:5], v[130:131] op_sel_hi:[1,0]
	v_pk_mul_f32 v[134:135], v[152:153], v[134:135]
	v_pk_mul_f32 v[152:153], v[0:1], v[130:131] op_sel_hi:[1,0]
	v_pk_mul_f32 v[130:131], v[2:3], v[130:131] op_sel_hi:[1,0]
	v_pk_mul_f32 v[158:159], v[158:159], v[160:161]
	v_pk_mul_f32 v[160:161], v[154:155], v[130:131]
	v_pk_mul_f32 v[156:157], v[156:157], v[152:153]
	s_waitcnt vmcnt(6)
	v_mov_b32_e32 v152, v246
	v_mov_b32_e32 v153, v247
	v_mov_b32_e32 v154, v248
	v_mov_b32_e32 v155, v249
	s_nop 0
	v_mov_b32_e32 v128, v250
	v_mov_b32_e32 v129, v251
	v_mov_b32_e32 v130, v252
	v_mov_b32_e32 v131, v253
	v_mov_b32_e32 v162, v153
	v_mov_b32_e32 v163, v155
	v_mov_b32_e32 v166, v129
	v_mov_b32_e32 v167, v131
	v_pk_mul_f32 v[164:165], v[162:163], v[156:157]
	v_pk_mul_f32 v[168:169], v[166:167], v[160:161]
	v_mov_b32_e32 v129, v130
	v_mov_b32_e32 v153, v154
	v_pk_fma_f32 v[130:131], v[128:129], v[134:135], v[168:169] neg_lo:[0,0,1] neg_hi:[0,0,1]
	v_pk_fma_f32 v[154:155], v[152:153], v[158:159], v[164:165] neg_lo:[0,0,1] neg_hi:[0,0,1]
	v_pk_mul_f32 v[152:153], v[152:153], v[156:157]
	v_pk_mul_f32 v[128:129], v[128:129], v[160:161]
	s_nop 0
	v_pk_fma_f32 v[128:129], v[166:167], v[134:135], v[128:129]
	v_pk_fma_f32 v[134:135], v[162:163], v[158:159], v[152:153]
	v_cvt_pk_bf16_f32 v152, v154, v155
	v_cvt_pk_bf16_f32 v153, v130, v131
	v_cvt_pk_bf16_f32 v130, v134, v135
	v_cvt_pk_bf16_f32 v131, v128, v129
	global_store_dwordx2 v[132:133], v[152:153], off offset:64
	global_store_dwordx2 v[132:133], v[130:131], off offset:96
